# GEMM K-loops: per-segment s_setprio toggling removed; one static priority raise for waves 4-7 set before each tile's K-loop
# speedup vs baseline: 1.0158x; 1.0158x over previous
; #define PG8_STAGE(bufoff, gbase, voff) do { _Pragma("unroll") for (int _i = 0; _i < 2; ++_i) \
;     __builtin_amdgcn_global_load_lds((const unsigned*)((const char*)(gbase) + (voff)[_i]), (LAS unsigned*)(lds + (bufoff) + ldsw + _i * 8192), 16, 0, 0); } while (0)
; #define PG8_LDA(dst, b, h) do { _Pragma("unroll") for (int m = 0; m < 4; ++m) _Pragma("unroll") for (int k = 0; k < 2; ++k) dst[m][k] = *(const LAS bf16x8*)(lds + PG8_SA(b, h) + aoff + m * 2048 + k * 1024); } while (0)
; #define PG8_LDB(dst, b, h) do { _Pragma("unroll") for (int n = 0; n < 2; ++n) _Pragma("unroll") for (int k = 0; k < 2; ++k) dst[n][k] = *(const LAS bf16x8*)(lds + PG8_SB(b, h) + boff + n * 2048 + k * 1024); } while (0)
; #define PG8_WAIT_L(n) asm volatile("s_waitcnt lgkmcnt(" #n ")" ::: "memory")
; #define PG8_BAR __builtin_amdgcn_s_barrier()
; #define PG8_SCHED __builtin_amdgcn_sched_barrier(0)
; template <class Epi>
; DI void gemm_phase(int wv, LAS unsigned char* lds, const Gemm g, const StaticOrder& S, const Epi& E) {
;     ...
;     const bool has_next = S.next(ui + 1, nxt);
;     const char* nA = has_next ? (const char*)g.A + (size_t)nxt.pm * tstep : cA; const char* nB = has_next ? (const char*)g.Bt + (size_t)nxt.pn * tstep : cB;
;     for (int t = 0; t < nt; t += 2) {
;       const bool last = (t == nt - 2);
;       const char* a1 = cA + (size_t)(t + 1) * kstep;
;       const char* a2 = last ? nA : cA + (size_t)(t + 2) * kstep; const char* b2 = last ? nB : cB + (size_t)(t + 2) * kstep;
;       const char* a3 = a2 + kstep; const char* b3 = b2 + kstep;
;       PG8_LDB(B0, 0, 0); PG8_SCHED; PG8_LDA(At, 0, 0); PG8_STAGE(PG8_SA(1, 1), a1 + hstep, voffA);
;       PG8_WAIT_L(8); PG8_BAR; PG8_WAIT_L(0); PG8_MMA(0, 0, At, B0); PG8_BAR; PG8_SCHED;
;       PG8_LDB(B1, 0, 1); PG8_STAGE(PG8_SB(0, 0), b2, voffA);
;       PG8_BAR; PG8_WAIT_L(0); PG8_MMA(0, 1, At, B1); PG8_BAR;
;     ...
; #pragma unroll
;     for (int a = 0; a < 2; ++a)
; #pragma unroll
;       for (int b = 0; b < 2; ++b)
; #pragma unroll
;         for (int m = 0; m < 4; ++m)
; #pragma unroll
;           for (int n = 0; n < 2; ++n) acc[a][b][m][n] = (f32x4){0.f, 0.f, 0.f, 0.f};
;     cur = nxt; cA = nA; cB = nB; ++ui;
.LBB0_208:
	s_ashr_i32 s15, s14, 31
	s_lshl_b64 s[16:17], s[14:15], 19
	s_add_u32 s16, s76, s16
	v_cmp_lt_i64_e64 s[6:7], s[6:7], v[196:197]
	s_addc_u32 s17, s77, s17
	s_and_b64 s[18:19], s[6:7], exec
	s_cselect_b32 s15, s17, s21
	s_cselect_b32 s54, s16, s20
	s_ashr_i32 s13, s12, 31
	s_lshl_b64 s[18:19], s[12:13], 19
	s_add_u32 s18, s31, s18
	s_addc_u32 s19, s33, s19
	s_and_b64 s[24:25], s[6:7], exec
	s_cselect_b32 s13, s19, s23
	s_cselect_b32 s57, s18, s22
	s_add_u32 s20, s20, 0x40080
	s_addc_u32 s21, s21, 0
	s_add_u32 s60, s22, 0x100
	v_mov_b32_e32 v0, 0
	s_addc_u32 s61, s23, 0
	s_mov_b32 s62, -2
	v_mov_b32_e32 v1, v0
	v_mov_b64_e32 v[2:3], v[0:1]
	v_mov_b64_e32 v[4:5], v[0:1]
	v_mov_b64_e32 v[6:7], v[0:1]
	v_mov_b64_e32 v[8:9], v[0:1]
	v_mov_b64_e32 v[10:11], v[0:1]
	v_mov_b64_e32 v[12:13], v[0:1]
	v_mov_b64_e32 v[14:15], v[0:1]
	v_mov_b64_e32 v[16:17], v[0:1]
	v_mov_b64_e32 v[18:19], v[0:1]
	v_mov_b64_e32 v[20:21], v[0:1]
	v_mov_b64_e32 v[22:23], v[0:1]
	v_mov_b64_e32 v[24:25], v[0:1]
	v_mov_b64_e32 v[26:27], v[0:1]
	v_mov_b64_e32 v[28:29], v[0:1]
	v_mov_b64_e32 v[30:31], v[0:1]
	v_mov_b64_e32 v[34:35], v[0:1]
	v_mov_b64_e32 v[36:37], v[0:1]
	v_mov_b64_e32 v[38:39], v[0:1]
	v_mov_b64_e32 v[40:41], v[0:1]
	v_mov_b64_e32 v[42:43], v[0:1]
	v_mov_b64_e32 v[44:45], v[0:1]
	v_mov_b64_e32 v[46:47], v[0:1]
	v_mov_b64_e32 v[48:49], v[0:1]
	v_mov_b64_e32 v[50:51], v[0:1]
	v_mov_b64_e32 v[52:53], v[0:1]
	v_mov_b64_e32 v[54:55], v[0:1]
	v_mov_b64_e32 v[56:57], v[0:1]
	v_mov_b64_e32 v[58:59], v[0:1]
	v_mov_b64_e32 v[60:61], v[0:1]
	v_mov_b64_e32 v[62:63], v[0:1]
	v_mov_b64_e32 v[64:65], v[0:1]
	v_mov_b64_e32 v[66:67], v[0:1]
	v_mov_b64_e32 v[68:69], v[0:1]
	v_mov_b64_e32 v[70:71], v[0:1]
	v_mov_b64_e32 v[72:73], v[0:1]
	v_mov_b64_e32 v[74:75], v[0:1]
	v_mov_b64_e32 v[76:77], v[0:1]
	v_mov_b64_e32 v[78:79], v[0:1]
	v_mov_b64_e32 v[80:81], v[0:1]
	v_mov_b64_e32 v[82:83], v[0:1]
	v_mov_b64_e32 v[84:85], v[0:1]
	v_mov_b64_e32 v[86:87], v[0:1]
	v_mov_b64_e32 v[88:89], v[0:1]
	v_mov_b64_e32 v[90:91], v[0:1]
	v_mov_b64_e32 v[92:93], v[0:1]
	v_mov_b64_e32 v[94:95], v[0:1]
	v_mov_b64_e32 v[96:97], v[0:1]
	s_waitcnt vmcnt(0)
	v_mov_b64_e32 v[98:99], v[0:1]
	v_mov_b64_e32 v[100:101], v[0:1]
	v_mov_b64_e32 v[102:103], v[0:1]
	v_mov_b64_e32 v[104:105], v[0:1]
	v_mov_b64_e32 v[106:107], v[0:1]
	v_mov_b64_e32 v[108:109], v[0:1]
	v_mov_b64_e32 v[110:111], v[0:1]
	v_mov_b64_e32 v[112:113], v[0:1]
	v_mov_b64_e32 v[114:115], v[0:1]
	v_mov_b64_e32 v[116:117], v[0:1]
	v_mov_b64_e32 v[118:119], v[0:1]
	v_mov_b64_e32 v[120:121], v[0:1]
	v_mov_b64_e32 v[122:123], v[0:1]
	v_mov_b64_e32 v[124:125], v[0:1]
	v_mov_b64_e32 v[126:127], v[0:1]
	v_mov_b64_e32 v[128:129], v[0:1]
	s_cmpk_lt_u32 s69, 0x100
	s_cbranch_scc1 .Lgprio_a
	s_setprio 1
.Lgprio_a:
.LBB0_209:
	s_add_u32 s22, s20, 0xfffc0080
	s_addc_u32 s23, s21, -1
	s_add_i32 s63, 0, 0x10000
	v_add_u32_e32 v142, s63, v193
	ds_read_b128 v[130:133], v142
	ds_read_b128 v[134:137], v142 offset:1024
	ds_read_b128 v[138:141], v142 offset:2048
	ds_read_b128 v[142:145], v142 offset:3072
	s_cmp_eq_u32 s62, 12
	s_cselect_b32 s25, s15, s23
	s_cselect_b32 s24, s54, s22
	s_cselect_b32 s23, s13, s61
	s_cselect_b32 s22, s57, s60
	v_lshl_add_u64 v[206:207], s[20:21], 0, v[166:167]
	s_add_i32 m0, s29, 0xc000
	ds_read_b128 v[146:149], v205
	ds_read_b128 v[150:153], v205 offset:1024
	ds_read_b128 v[154:157], v205 offset:2048
	ds_read_b128 v[158:161], v205 offset:3072
	ds_read_b128 v[170:173], v205 offset:4096
	ds_read_b128 v[174:177], v205 offset:5120
	ds_read_b128 v[178:181], v205 offset:6144
	ds_read_b128 v[182:185], v205 offset:7168
	global_load_lds_dwordx4 v[206:207], off
	v_lshl_add_u64 v[206:207], s[20:21], 0, v[168:169]
	s_add_i32 m0, s29, 0xe000
	s_nop 0
	global_load_lds_dwordx4 v[206:207], off
	s_waitcnt lgkmcnt(8)
	s_barrier
	s_waitcnt lgkmcnt(0)
	s_waitcnt lgkmcnt(0)
	v_mfma_f32_16x16x32_f16 v[126:129], v[130:133], v[146:149], v[126:129]
	v_mfma_f32_16x16x32_f16 v[122:125], v[138:141], v[146:149], v[122:125]
	v_mfma_f32_16x16x32_f16 v[118:121], v[130:133], v[154:157], v[118:121]
	v_mfma_f32_16x16x32_f16 v[114:117], v[138:141], v[154:157], v[114:117]
	v_mfma_f32_16x16x32_f16 v[110:113], v[130:133], v[170:173], v[110:113]
	v_mfma_f32_16x16x32_f16 v[106:109], v[138:141], v[170:173], v[106:109]
	v_mfma_f32_16x16x32_f16 v[102:105], v[130:133], v[178:181], v[102:105]
	v_mfma_f32_16x16x32_f16 v[98:101], v[138:141], v[178:181], v[98:101]
	v_mfma_f32_16x16x32_f16 v[126:129], v[134:137], v[150:153], v[126:129]
	v_mfma_f32_16x16x32_f16 v[122:125], v[142:145], v[150:153], v[122:125]
	v_mfma_f32_16x16x32_f16 v[118:121], v[134:137], v[158:161], v[118:121]
	v_mfma_f32_16x16x32_f16 v[114:117], v[142:145], v[158:161], v[114:117]
	v_mfma_f32_16x16x32_f16 v[110:113], v[134:137], v[174:177], v[110:113]
	v_mfma_f32_16x16x32_f16 v[106:109], v[142:145], v[174:177], v[106:109]
	v_mfma_f32_16x16x32_f16 v[102:105], v[134:137], v[182:185], v[102:105]
	v_mfma_f32_16x16x32_f16 v[98:101], v[142:145], v[182:185], v[98:101]
	s_barrier
	s_add_i32 s70, 0, 0x14000
	s_add_i32 s63, s63, s27
	v_add_u32_e32 v186, s70, v193
	v_lshl_add_u64 v[222:223], s[22:23], 0, v[162:163]
	s_mov_b32 m0, s63
	ds_read_b128 v[206:209], v186
	ds_read_b128 v[210:213], v186 offset:1024
	ds_read_b128 v[214:217], v186 offset:2048
	ds_read_b128 v[218:221], v186 offset:3072
	global_load_lds_dwordx4 v[222:223], off
	v_lshl_add_u64 v[224:225], s[22:23], 0, v[164:165]
	s_add_i32 m0, s63, 0x2000
	s_nop 0
	global_load_lds_dwordx4 v[224:225], off
	s_barrier
; #define PG8_STAGE(bufoff, gbase, voff) do { _Pragma("unroll") for (int _i = 0; _i < 2; ++_i) \
;     __builtin_amdgcn_global_load_lds((const unsigned*)((const char*)(gbase) + (voff)[_i]), (LAS unsigned*)(lds + (bufoff) + ldsw + _i * 8192), 16, 0, 0); } while (0)
; #define PG8_LDA(dst, b, h) do { _Pragma("unroll") for (int m = 0; m < 4; ++m) _Pragma("unroll") for (int k = 0; k < 2; ++k) dst[m][k] = *(const LAS bf16x8*)(lds + PG8_SA(b, h) + aoff + m * 2048 + k * 1024); } while (0)
; #define PG8_LDB(dst, b, h) do { _Pragma("unroll") for (int n = 0; n < 2; ++n) _Pragma("unroll") for (int k = 0; k < 2; ++k) dst[n][k] = *(const LAS bf16x8*)(lds + PG8_SB(b, h) + boff + n * 2048 + k * 1024); } while (0)
; #define PG8_WAIT_V(n) asm volatile("s_waitcnt vmcnt(" #n ")" ::: "memory")
; #define PG8_WAIT_L(n) asm volatile("s_waitcnt lgkmcnt(" #n ")" ::: "memory")
; #define PG8_BAR __builtin_amdgcn_s_barrier()
; #define PG8_SCHED __builtin_amdgcn_sched_barrier(0)
; template <class Epi>
; DI void gemm_phase(int wv, LAS unsigned char* lds, const Gemm g, const StaticOrder& S, const Epi& E) {
;     ...
;       PG8_BAR; PG8_WAIT_L(0); PG8_MMA(0, 1, At, B1); PG8_BAR;
;       PG8_LDA(At, 0, 1); PG8_STAGE(PG8_SA(0, 0), a2, voffA);
;       PG8_BAR; PG8_WAIT_L(0); PG8_MMA(1, 0, At, B0); PG8_BAR; PG8_SCHED;
;       PG8_STAGE(PG8_SB(0, 1), b2 + hstep, voffA);
;       PG8_WAIT_V(6); PG8_BAR; PG8_MMA(1, 1, At, B1); PG8_BAR;
;       PG8_LDB(B0, 1, 0); PG8_SCHED; PG8_LDA(At, 1, 0); PG8_STAGE(PG8_SA(0, 1), a2 + hstep, voffA);
;       PG8_WAIT_L(8); PG8_BAR; PG8_WAIT_L(0); PG8_MMA(0, 0, At, B0); PG8_BAR; PG8_SCHED;
	s_waitcnt lgkmcnt(0)
	s_waitcnt lgkmcnt(0)
	v_mfma_f32_16x16x32_f16 v[94:97], v[206:209], v[146:149], v[94:97]
	v_mfma_f32_16x16x32_f16 v[90:93], v[214:217], v[146:149], v[90:93]
	v_mfma_f32_16x16x32_f16 v[86:89], v[206:209], v[154:157], v[86:89]
	v_mfma_f32_16x16x32_f16 v[82:85], v[214:217], v[154:157], v[82:85]
	v_mfma_f32_16x16x32_f16 v[78:81], v[206:209], v[170:173], v[78:81]
	v_mfma_f32_16x16x32_f16 v[74:77], v[214:217], v[170:173], v[74:77]
	v_mfma_f32_16x16x32_f16 v[70:73], v[206:209], v[178:181], v[70:73]
	v_mfma_f32_16x16x32_f16 v[66:69], v[214:217], v[178:181], v[66:69]
	v_mfma_f32_16x16x32_f16 v[94:97], v[210:213], v[150:153], v[94:97]
	v_mfma_f32_16x16x32_f16 v[90:93], v[218:221], v[150:153], v[90:93]
	v_mfma_f32_16x16x32_f16 v[86:89], v[210:213], v[158:161], v[86:89]
	v_mfma_f32_16x16x32_f16 v[82:85], v[218:221], v[158:161], v[82:85]
	v_mfma_f32_16x16x32_f16 v[78:81], v[210:213], v[174:177], v[78:81]
	v_mfma_f32_16x16x32_f16 v[74:77], v[218:221], v[174:177], v[74:77]
	v_mfma_f32_16x16x32_f16 v[70:73], v[210:213], v[182:185], v[70:73]
	v_mfma_f32_16x16x32_f16 v[66:69], v[218:221], v[182:185], v[66:69]
	s_mov_b32 m0, s29
	v_lshl_add_u64 v[226:227], s[24:25], 0, v[162:163]
	s_barrier
	ds_read_b128 v[146:149], v205 offset:16384
	ds_read_b128 v[150:153], v205 offset:17408
	ds_read_b128 v[154:157], v205 offset:18432
	ds_read_b128 v[158:161], v205 offset:19456
	ds_read_b128 v[170:173], v205 offset:20480
	ds_read_b128 v[174:177], v205 offset:21504
	ds_read_b128 v[178:181], v205 offset:22528
	ds_read_b128 v[182:185], v205 offset:23552
	global_load_lds_dwordx4 v[226:227], off
	v_lshl_add_u64 v[230:231], s[24:25], 0, v[164:165]
	s_mov_b32 m0, s34
	s_nop 0
	global_load_lds_dwordx4 v[230:231], off
	s_barrier
	s_waitcnt lgkmcnt(0)
	s_waitcnt lgkmcnt(0)
	v_mfma_f32_16x16x32_f16 v[62:65], v[130:133], v[146:149], v[62:65]
	v_mfma_f32_16x16x32_f16 v[58:61], v[138:141], v[146:149], v[58:61]
	v_mfma_f32_16x16x32_f16 v[54:57], v[130:133], v[154:157], v[54:57]
	v_mfma_f32_16x16x32_f16 v[50:53], v[138:141], v[154:157], v[50:53]
	v_mfma_f32_16x16x32_f16 v[46:49], v[130:133], v[170:173], v[46:49]
	v_mfma_f32_16x16x32_f16 v[42:45], v[138:141], v[170:173], v[42:45]
	v_mfma_f32_16x16x32_f16 v[38:41], v[130:133], v[178:181], v[38:41]
	v_mfma_f32_16x16x32_f16 v[34:37], v[138:141], v[178:181], v[34:37]
	v_mfma_f32_16x16x32_f16 v[62:65], v[134:137], v[150:153], v[62:65]
	v_mfma_f32_16x16x32_f16 v[58:61], v[142:145], v[150:153], v[58:61]
	v_mfma_f32_16x16x32_f16 v[54:57], v[134:137], v[158:161], v[54:57]
	v_mfma_f32_16x16x32_f16 v[50:53], v[142:145], v[158:161], v[50:53]
	v_mfma_f32_16x16x32_f16 v[46:49], v[134:137], v[174:177], v[46:49]
	v_mfma_f32_16x16x32_f16 v[42:45], v[142:145], v[174:177], v[42:45]
	v_mfma_f32_16x16x32_f16 v[38:41], v[134:137], v[182:185], v[38:41]
	v_mfma_f32_16x16x32_f16 v[34:37], v[142:145], v[182:185], v[34:37]
	s_barrier
	s_add_u32 s64, s22, 0x40000
	s_addc_u32 s65, s23, 0
	s_add_i32 s63, s70, s27
	v_lshl_add_u64 v[130:131], s[64:65], 0, v[162:163]
	s_mov_b32 m0, s63
	s_nop 0
	global_load_lds_dwordx4 v[130:131], off
	v_lshl_add_u64 v[130:131], s[64:65], 0, v[164:165]
	s_add_i32 m0, s63, 0x2000
	s_nop 0
	global_load_lds_dwordx4 v[130:131], off
	s_waitcnt vmcnt(6)
	s_barrier
	v_mfma_f32_16x16x32_f16 v[28:31], v[206:209], v[146:149], v[28:31]
	v_mfma_f32_16x16x32_f16 v[24:27], v[214:217], v[146:149], v[24:27]
	v_mfma_f32_16x16x32_f16 v[20:23], v[206:209], v[154:157], v[20:23]
	v_mfma_f32_16x16x32_f16 v[16:19], v[214:217], v[154:157], v[16:19]
	v_mfma_f32_16x16x32_f16 v[12:15], v[206:209], v[170:173], v[12:15]
	v_mfma_f32_16x16x32_f16 v[8:11], v[214:217], v[170:173], v[8:11]
	v_mfma_f32_16x16x32_f16 v[4:7], v[206:209], v[178:181], v[4:7]
	v_mfma_f32_16x16x32_f16 v[0:3], v[214:217], v[178:181], v[0:3]
	v_mfma_f32_16x16x32_f16 v[28:31], v[210:213], v[150:153], v[28:31]
	v_mfma_f32_16x16x32_f16 v[24:27], v[218:221], v[150:153], v[24:27]
	v_mfma_f32_16x16x32_f16 v[20:23], v[210:213], v[158:161], v[20:23]
	v_mfma_f32_16x16x32_f16 v[16:19], v[218:221], v[158:161], v[16:19]
	v_mfma_f32_16x16x32_f16 v[12:15], v[210:213], v[174:177], v[12:15]
	v_mfma_f32_16x16x32_f16 v[8:11], v[218:221], v[174:177], v[8:11]
	v_mfma_f32_16x16x32_f16 v[4:7], v[210:213], v[182:185], v[4:7]
	v_mfma_f32_16x16x32_f16 v[0:3], v[218:221], v[182:185], v[0:3]
	s_add_i32 s63, 0, 0x18000
	v_add_u32_e32 v142, s63, v193
	s_barrier
	ds_read_b128 v[130:133], v142
	ds_read_b128 v[134:137], v142 offset:1024
	ds_read_b128 v[138:141], v142 offset:2048
	ds_read_b128 v[142:145], v142 offset:3072
	s_add_u32 s24, s24, 0x40000
	s_addc_u32 s25, s25, 0
	s_mov_b32 m0, s35
	v_lshl_add_u64 v[206:207], s[24:25], 0, v[162:163]
	ds_read_b128 v[146:149], v205 offset:32768
	ds_read_b128 v[150:153], v205 offset:33792
	ds_read_b128 v[154:157], v205 offset:34816
	ds_read_b128 v[158:161], v205 offset:35840
	ds_read_b128 v[170:173], v205 offset:36864
	ds_read_b128 v[174:177], v205 offset:37888
	ds_read_b128 v[178:181], v205 offset:38912
	ds_read_b128 v[182:185], v205 offset:39936
	global_load_lds_dwordx4 v[206:207], off
	v_lshl_add_u64 v[206:207], s[24:25], 0, v[164:165]
	s_mov_b32 m0, s36
	s_nop 0
	global_load_lds_dwordx4 v[206:207], off
	s_waitcnt lgkmcnt(8)
	s_barrier
; #define PG8_STAGE(bufoff, gbase, voff) do { _Pragma("unroll") for (int _i = 0; _i < 2; ++_i) \
;     __builtin_amdgcn_global_load_lds((const unsigned*)((const char*)(gbase) + (voff)[_i]), (LAS unsigned*)(lds + (bufoff) + ldsw + _i * 8192), 16, 0, 0); } while (0)
; #define PG8_LDA(dst, b, h) do { _Pragma("unroll") for (int m = 0; m < 4; ++m) _Pragma("unroll") for (int k = 0; k < 2; ++k) dst[m][k] = *(const LAS bf16x8*)(lds + PG8_SA(b, h) + aoff + m * 2048 + k * 1024); } while (0)
; #define PG8_LDB(dst, b, h) do { _Pragma("unroll") for (int n = 0; n < 2; ++n) _Pragma("unroll") for (int k = 0; k < 2; ++k) dst[n][k] = *(const LAS bf16x8*)(lds + PG8_SB(b, h) + boff + n * 2048 + k * 1024); } while (0)
; #define PG8_WAIT_L(n) asm volatile("s_waitcnt lgkmcnt(" #n ")" ::: "memory")
; #define PG8_BAR __builtin_amdgcn_s_barrier()
; #define PG8_SCHED __builtin_amdgcn_sched_barrier(0)
; template <class Epi>
; DI void gemm_phase(int wv, LAS unsigned char* lds, const Gemm g, const StaticOrder& S, const Epi& E) {
;     ...
;       PG8_WAIT_L(8); PG8_BAR; PG8_WAIT_L(0); PG8_MMA(0, 0, At, B0); PG8_BAR; PG8_SCHED;
;       PG8_LDB(B1, 1, 1); PG8_STAGE(PG8_SB(1, 0), b3, voffA);
;       PG8_BAR; PG8_WAIT_L(0); PG8_MMA(0, 1, At, B1); PG8_BAR;
;       PG8_LDA(At, 1, 1); PG8_STAGE(PG8_SA(1, 0), a3, voffA);
;       PG8_BAR; PG8_WAIT_L(0); PG8_MMA(1, 0, At, B0); PG8_BAR; PG8_SCHED;
	s_waitcnt lgkmcnt(0)
	s_waitcnt lgkmcnt(0)
	v_mfma_f32_16x16x32_f16 v[126:129], v[130:133], v[146:149], v[126:129]
	v_mfma_f32_16x16x32_f16 v[122:125], v[138:141], v[146:149], v[122:125]
	v_mfma_f32_16x16x32_f16 v[118:121], v[130:133], v[154:157], v[118:121]
	v_mfma_f32_16x16x32_f16 v[114:117], v[138:141], v[154:157], v[114:117]
	v_mfma_f32_16x16x32_f16 v[110:113], v[130:133], v[170:173], v[110:113]
	v_mfma_f32_16x16x32_f16 v[106:109], v[138:141], v[170:173], v[106:109]
	v_mfma_f32_16x16x32_f16 v[102:105], v[130:133], v[178:181], v[102:105]
	v_mfma_f32_16x16x32_f16 v[98:101], v[138:141], v[178:181], v[98:101]
	v_mfma_f32_16x16x32_f16 v[126:129], v[134:137], v[150:153], v[126:129]
	v_mfma_f32_16x16x32_f16 v[122:125], v[142:145], v[150:153], v[122:125]
	v_mfma_f32_16x16x32_f16 v[118:121], v[134:137], v[158:161], v[118:121]
	v_mfma_f32_16x16x32_f16 v[114:117], v[142:145], v[158:161], v[114:117]
	v_mfma_f32_16x16x32_f16 v[110:113], v[134:137], v[174:177], v[110:113]
	v_mfma_f32_16x16x32_f16 v[106:109], v[142:145], v[174:177], v[106:109]
	v_mfma_f32_16x16x32_f16 v[102:105], v[134:137], v[182:185], v[102:105]
	v_mfma_f32_16x16x32_f16 v[98:101], v[142:145], v[182:185], v[98:101]
	s_barrier
	s_add_i32 s24, 0, 0x1c000
	s_add_i32 s25, s63, s27
	v_add_u32_e32 v186, s24, v193
	v_lshl_add_u64 v[222:223], v[222:223], 0, s[2:3]
	s_mov_b32 m0, s25
	ds_read_b128 v[206:209], v186
	ds_read_b128 v[210:213], v186 offset:1024
	ds_read_b128 v[214:217], v186 offset:2048
	ds_read_b128 v[218:221], v186 offset:3072
	global_load_lds_dwordx4 v[222:223], off
	v_lshl_add_u64 v[222:223], v[224:225], 0, s[2:3]
	s_add_i32 m0, s25, 0x2000
	s_nop 0
	global_load_lds_dwordx4 v[222:223], off
	s_barrier
	s_waitcnt lgkmcnt(0)
	s_waitcnt lgkmcnt(0)
	v_mfma_f32_16x16x32_f16 v[94:97], v[206:209], v[146:149], v[94:97]
	v_mfma_f32_16x16x32_f16 v[90:93], v[214:217], v[146:149], v[90:93]
	v_mfma_f32_16x16x32_f16 v[86:89], v[206:209], v[154:157], v[86:89]
	v_mfma_f32_16x16x32_f16 v[82:85], v[214:217], v[154:157], v[82:85]
	v_mfma_f32_16x16x32_f16 v[78:81], v[206:209], v[170:173], v[78:81]
	v_mfma_f32_16x16x32_f16 v[74:77], v[214:217], v[170:173], v[74:77]
	v_mfma_f32_16x16x32_f16 v[70:73], v[206:209], v[178:181], v[70:73]
	v_mfma_f32_16x16x32_f16 v[66:69], v[214:217], v[178:181], v[66:69]
	v_mfma_f32_16x16x32_f16 v[94:97], v[210:213], v[150:153], v[94:97]
	v_mfma_f32_16x16x32_f16 v[90:93], v[218:221], v[150:153], v[90:93]
	v_mfma_f32_16x16x32_f16 v[86:89], v[210:213], v[158:161], v[86:89]
	v_mfma_f32_16x16x32_f16 v[82:85], v[218:221], v[158:161], v[82:85]
	v_mfma_f32_16x16x32_f16 v[78:81], v[210:213], v[174:177], v[78:81]
	v_mfma_f32_16x16x32_f16 v[74:77], v[218:221], v[174:177], v[74:77]
	v_mfma_f32_16x16x32_f16 v[70:73], v[210:213], v[182:185], v[70:73]
	v_mfma_f32_16x16x32_f16 v[66:69], v[218:221], v[182:185], v[66:69]
	s_mov_b32 m0, s37
	v_lshl_add_u64 v[222:223], v[226:227], 0, s[2:3]
	s_barrier
	ds_read_b128 v[146:149], v205 offset:49152
	ds_read_b128 v[150:153], v205 offset:50176
	ds_read_b128 v[154:157], v205 offset:51200
	ds_read_b128 v[158:161], v205 offset:52224
	ds_read_b128 v[170:173], v205 offset:53248
	ds_read_b128 v[174:177], v205 offset:54272
	ds_read_b128 v[178:181], v205 offset:55296
	ds_read_b128 v[182:185], v205 offset:56320
	global_load_lds_dwordx4 v[222:223], off
	v_lshl_add_u64 v[222:223], v[230:231], 0, s[2:3]
	s_mov_b32 m0, s38
	s_nop 0
	global_load_lds_dwordx4 v[222:223], off
	s_barrier
; #define LAS __attribute__((address_space(3)))
; #define PG8_STAGE(bufoff, gbase, voff) do { _Pragma("unroll") for (int _i = 0; _i < 2; ++_i) \
;     __builtin_amdgcn_global_load_lds((const unsigned*)((const char*)(gbase) + (voff)[_i]), (LAS unsigned*)(lds + (bufoff) + ldsw + _i * 8192), 16, 0, 0); } while (0)
; #define PG8_WAIT_V(n) asm volatile("s_waitcnt vmcnt(" #n ")" ::: "memory")
; #define PG8_WAIT_L(n) asm volatile("s_waitcnt lgkmcnt(" #n ")" ::: "memory")
; #define PG8_BAR __builtin_amdgcn_s_barrier()
; #define PG8_SCHED __builtin_amdgcn_sched_barrier(0)
; template <class Epi>
; DI void gemm_phase(int wv, LAS unsigned char* lds, const Gemm g, const StaticOrder& S, const Epi& E) {
;     ...
;       PG8_BAR; PG8_WAIT_L(0); PG8_MMA(1, 0, At, B0); PG8_BAR; PG8_SCHED;
;       PG8_STAGE(PG8_SB(1, 1), b3 + hstep, voffA);
;       PG8_WAIT_V(6); PG8_BAR; PG8_MMA(1, 1, At, B1); PG8_BAR;
;     }
;   DI void operator()(const f32x4 (&acc)[2][2][4][2], const pg8::Unit& u, int wr, int wc, int fr, int fq, LAS unsigned char* lds, int ui, int wid) const {
;     const int colg = u.pn * 256 + wc * 32 + 8 * fq, hcol = u.pn * 128 + wc * 32 + 8 * fq;
;     f32x4 c1g[2], c2g[2], c1u[2], c2u[2];
;     int fq_ = fq, fr_ = fr; asm volatile("" : "+v"(fq_), "+v"(fr_));
;     const LAS float* cl = (const LAS float*)(lds + 139264 + (ui & 1) * 2048) + wc * 32 + 8 * fq_;
; #pragma unroll
;     for (int n = 0; n < 2; ++n) { c1g[n] = *(const LAS f32x4*)(cl + 4 * n); c2g[n] = *(const LAS f32x4*)(cl + 256 + 4 * n); c1u[n] = *(const LAS f32x4*)(cl + 128 + 4 * n); c2u[n] = *(const LAS f32x4*)(cl + 256 + 128 + 4 * n); }
;     float ra[8], rb[8];
;     const LAS float* sl = (const LAS float*)(lds + 131072 + wid * 1024);
; #pragma unroll
;     for (int i = 0; i < 8; ++i) { typedef float f32x2_ __attribute__((ext_vector_type(2))); const f32x2_ sv = *(const LAS f32x2_*)(sl + (i >> 2) * 128 + ((i & 3) * 16 + fr_) * 2);
;       const float mu = sv.x * (1.0f / 1024.0f), var = fmaxf(sv.y * (1.0f / 1024.0f) - mu * mu, 0.f), rstd = rsqrtf(var + 1e-5f); ra[i] = rstd; rb[i] = -rstd * mu; }
; #pragma unroll
;     for (int ai = 0; ai < 2; ++ai)
; #pragma unroll
;       for (int m = 0; m < 4; ++m) {
;         const int row = u.pm * 256 + ai * 128 + wr * 64 + m * 16 + fr; const float a = ra[ai * 4 + m], bb = rb[ai * 4 + m];
	s_waitcnt lgkmcnt(0)
	s_waitcnt lgkmcnt(0)
	v_mfma_f32_16x16x32_f16 v[62:65], v[130:133], v[146:149], v[62:65]
	v_mfma_f32_16x16x32_f16 v[58:61], v[138:141], v[146:149], v[58:61]
	v_mfma_f32_16x16x32_f16 v[54:57], v[130:133], v[154:157], v[54:57]
	v_mfma_f32_16x16x32_f16 v[50:53], v[138:141], v[154:157], v[50:53]
	v_mfma_f32_16x16x32_f16 v[46:49], v[130:133], v[170:173], v[46:49]
	v_mfma_f32_16x16x32_f16 v[42:45], v[138:141], v[170:173], v[42:45]
	v_mfma_f32_16x16x32_f16 v[38:41], v[130:133], v[178:181], v[38:41]
	v_mfma_f32_16x16x32_f16 v[34:37], v[138:141], v[178:181], v[34:37]
	v_mfma_f32_16x16x32_f16 v[62:65], v[134:137], v[150:153], v[62:65]
	v_mfma_f32_16x16x32_f16 v[58:61], v[142:145], v[150:153], v[58:61]
	v_mfma_f32_16x16x32_f16 v[54:57], v[134:137], v[158:161], v[54:57]
	v_mfma_f32_16x16x32_f16 v[50:53], v[142:145], v[158:161], v[50:53]
	v_mfma_f32_16x16x32_f16 v[46:49], v[134:137], v[174:177], v[46:49]
	v_mfma_f32_16x16x32_f16 v[42:45], v[142:145], v[174:177], v[42:45]
	v_mfma_f32_16x16x32_f16 v[38:41], v[134:137], v[182:185], v[38:41]
	v_mfma_f32_16x16x32_f16 v[34:37], v[142:145], v[182:185], v[34:37]
	s_barrier
	s_add_u32 s22, s22, 0x40080
	s_addc_u32 s23, s23, 0
	s_add_i32 s24, s24, s27
	v_lshl_add_u64 v[130:131], s[22:23], 0, v[162:163]
	s_mov_b32 m0, s24
	s_nop 0
	global_load_lds_dwordx4 v[130:131], off
	v_lshl_add_u64 v[130:131], s[22:23], 0, v[164:165]
	s_add_i32 m0, s24, 0x2000
	s_nop 0
	global_load_lds_dwordx4 v[130:131], off
	s_waitcnt vmcnt(6)
	s_barrier
	v_mfma_f32_16x16x32_f16 v[28:31], v[206:209], v[146:149], v[28:31]
	v_mfma_f32_16x16x32_f16 v[24:27], v[214:217], v[146:149], v[24:27]
	v_mfma_f32_16x16x32_f16 v[20:23], v[206:209], v[154:157], v[20:23]
	v_mfma_f32_16x16x32_f16 v[16:19], v[214:217], v[154:157], v[16:19]
	v_mfma_f32_16x16x32_f16 v[12:15], v[206:209], v[170:173], v[12:15]
	v_mfma_f32_16x16x32_f16 v[8:11], v[214:217], v[170:173], v[8:11]
	v_mfma_f32_16x16x32_f16 v[4:7], v[206:209], v[178:181], v[4:7]
	v_mfma_f32_16x16x32_f16 v[0:3], v[214:217], v[178:181], v[0:3]
	v_mfma_f32_16x16x32_f16 v[28:31], v[210:213], v[150:153], v[28:31]
	v_mfma_f32_16x16x32_f16 v[24:27], v[218:221], v[150:153], v[24:27]
	v_mfma_f32_16x16x32_f16 v[20:23], v[210:213], v[158:161], v[20:23]
	v_mfma_f32_16x16x32_f16 v[16:19], v[218:221], v[158:161], v[16:19]
	v_mfma_f32_16x16x32_f16 v[12:15], v[210:213], v[174:177], v[12:15]
	v_mfma_f32_16x16x32_f16 v[8:11], v[218:221], v[174:177], v[8:11]
	v_mfma_f32_16x16x32_f16 v[4:7], v[210:213], v[182:185], v[4:7]
	v_mfma_f32_16x16x32_f16 v[0:3], v[218:221], v[182:185], v[0:3]
	s_add_i32 s62, s62, 2
	s_add_u32 s20, s20, 0x100
	s_addc_u32 s21, s21, 0
	s_add_u32 s60, s60, 0x100
	s_addc_u32 s61, s61, 0
	s_cmp_gt_u32 s62, 13
	s_barrier
	s_cbranch_scc0 .LBB0_209
	v_readlane_b32 s20, v253, 8
	v_readlane_b32 s21, v253, 9
	s_andn2_b64 vcc, exec, s[20:21]
	s_mov_b32 s22, 0x800000
	s_cbranch_vccnz .LBB0_213
	v_lshl_or_b32 v130, s49, 7, v203
	v_lshl_add_u32 v134, s50, 8, v191
	v_ashrrev_i32_e32 v131, 31, v130
	v_mov_b64_e32 v[132:133], s[10:11]
	v_or_b32_e32 v136, 16, v134
	v_or_b32_e32 v137, 32, v134
	v_or_b32_e32 v138, 48, v134
	v_add_u32_e32 v139, 0x80, v134
	v_add_u32_e32 v140, 0x90, v134
	v_add_u32_e32 v141, 0xa0, v134
	v_add_u32_e32 v142, 0xb0, v134
	v_mad_i64_i32 v[134:135], s[20:21], v134, s91, v[132:133]
	v_lshlrev_b64 v[130:131], 1, v[130:131]
	v_lshl_add_u64 v[170:171], v[134:135], 0, v[130:131]
	v_mad_i64_i32 v[134:135], s[20:21], v136, s91, v[132:133]
	v_lshl_add_u64 v[172:173], v[134:135], 0, v[130:131]
	v_mad_i64_i32 v[134:135], s[20:21], v137, s91, v[132:133]
	v_lshl_add_u64 v[174:175], v[134:135], 0, v[130:131]
	v_mad_i64_i32 v[134:135], s[20:21], v138, s91, v[132:133]
	v_lshl_add_u64 v[176:177], v[134:135], 0, v[130:131]
	v_mad_i64_i32 v[134:135], s[20:21], v139, s91, v[132:133]
	s_lshl_b32 s13, s51, 11
	v_lshl_add_u64 v[178:179], v[134:135], 0, v[130:131]
	v_mad_i64_i32 v[134:135], s[20:21], v140, s91, v[132:133]
	v_readlane_b32 s44, v252, 2
	s_and_b32 s13, s13, 0x800
	v_lshl_add_u64 v[180:181], v[134:135], 0, v[130:131]
	v_mad_i64_i32 v[134:135], s[20:21], v141, s91, v[132:133]
	v_mad_i64_i32 v[132:133], s[20:21], v142, s91, v[132:133]
	v_readlane_b32 s50, v252, 8
	s_add_i32 s13, s40, s13
	v_lshl_add_u64 v[182:183], v[134:135], 0, v[130:131]
	v_lshl_add_u64 v[184:185], v[132:133], 0, v[130:131]
	s_mov_b32 s20, 0x3a800000
	s_mov_b32 s15, s50
	v_readlane_b32 s45, v252, 3
	v_readlane_b32 s46, v252, 4
	v_readlane_b32 s47, v252, 5
	v_readlane_b32 s48, v252, 6
	v_readlane_b32 s49, v252, 7
	v_readlane_b32 s51, v252, 9

; #define PG8_STAGE(bufoff, gbase, voff) do { _Pragma("unroll") for (int _i = 0; _i < 2; ++_i) \
;     __builtin_amdgcn_global_load_lds((const unsigned*)((const char*)(gbase) + (voff)[_i]), (LAS unsigned*)(lds + (bufoff) + ldsw + _i * 8192), 16, 0, 0); } while (0)
; #define PG8_LDA(dst, b, h) do { _Pragma("unroll") for (int m = 0; m < 4; ++m) _Pragma("unroll") for (int k = 0; k < 2; ++k) dst[m][k] = *(const LAS bf16x8*)(lds + PG8_SA(b, h) + aoff + m * 2048 + k * 1024); } while (0)
; #define PG8_LDB(dst, b, h) do { _Pragma("unroll") for (int n = 0; n < 2; ++n) _Pragma("unroll") for (int k = 0; k < 2; ++k) dst[n][k] = *(const LAS bf16x8*)(lds + PG8_SB(b, h) + boff + n * 2048 + k * 1024); } while (0)
; #define PG8_WAIT_L(n) asm volatile("s_waitcnt lgkmcnt(" #n ")" ::: "memory")
; #define PG8_BAR __builtin_amdgcn_s_barrier()
; #define PG8_SCHED __builtin_amdgcn_sched_barrier(0)
; template <class Epi>
; DI void gemm_phase(int wv, LAS unsigned char* lds, const Gemm g, const StaticOrder& S, const Epi& E) {
;     ...
;     const bool has_next = S.next(ui + 1, nxt);
;     const char* nA = has_next ? (const char*)g.A + (size_t)nxt.pm * tstep : cA; const char* nB = has_next ? (const char*)g.Bt + (size_t)nxt.pn * tstep : cB;
;     for (int t = 0; t < nt; t += 2) {
;       const bool last = (t == nt - 2);
;       const char* a1 = cA + (size_t)(t + 1) * kstep;
;       const char* a2 = last ? nA : cA + (size_t)(t + 2) * kstep; const char* b2 = last ? nB : cB + (size_t)(t + 2) * kstep;
;       const char* a3 = a2 + kstep; const char* b3 = b2 + kstep;
;       PG8_LDB(B0, 0, 0); PG8_SCHED; PG8_LDA(At, 0, 0); PG8_STAGE(PG8_SA(1, 1), a1 + hstep, voffA);
;       PG8_WAIT_L(8); PG8_BAR; PG8_WAIT_L(0); PG8_MMA(0, 0, At, B0); PG8_BAR; PG8_SCHED;
;       PG8_LDB(B1, 0, 1); PG8_STAGE(PG8_SB(0, 0), b2, voffA);
;       PG8_BAR; PG8_WAIT_L(0); PG8_MMA(0, 1, At, B1); PG8_BAR;
;     ...
; #pragma unroll
;     for (int a = 0; a < 2; ++a)
; #pragma unroll
;       for (int b = 0; b < 2; ++b)
; #pragma unroll
;         for (int m = 0; m < 4; ++m)
; #pragma unroll
;           for (int n = 0; n < 2; ++n) acc[a][b][m][n] = (f32x4){0.f, 0.f, 0.f, 0.f};
;     cur = nxt; cA = nA; cB = nB; ++ui;
.LBB0_292:
	s_ashr_i32 s21, s20, 31
	s_lshl_b64 s[22:23], s[20:21], 19
	s_add_u32 s22, s76, s22
	s_addc_u32 s23, s77, s23
	s_and_b64 s[24:25], s[6:7], exec
	s_cselect_b32 s21, s23, s31
	s_cselect_b32 s29, s22, s30
	s_ashr_i32 s19, s18, 31
	s_lshl_b64 s[24:25], s[18:19], 19
	s_add_u32 s24, s82, s24
	s_addc_u32 s25, s83, s25
	s_and_b64 s[36:37], s[6:7], exec
	s_cselect_b32 s19, s25, s35
	s_cselect_b32 s33, s24, s34
	s_add_u32 s30, s30, 0x40080
	s_addc_u32 s31, s31, 0
	s_add_u32 s49, s34, 0x100
	v_mov_b32_e32 v0, 0
	s_addc_u32 s50, s35, 0
	s_mov_b32 s51, -2
	v_mov_b32_e32 v1, v0
	v_mov_b64_e32 v[2:3], v[0:1]
	v_mov_b64_e32 v[4:5], v[0:1]
	v_mov_b64_e32 v[6:7], v[0:1]
	v_mov_b64_e32 v[16:17], v[0:1]
	v_mov_b64_e32 v[18:19], v[0:1]
	v_mov_b64_e32 v[20:21], v[0:1]
	v_mov_b64_e32 v[22:23], v[0:1]
	v_mov_b64_e32 v[34:35], v[0:1]
	v_mov_b64_e32 v[36:37], v[0:1]
	v_mov_b64_e32 v[38:39], v[0:1]
	v_mov_b64_e32 v[40:41], v[0:1]
	v_mov_b64_e32 v[50:51], v[0:1]
	v_mov_b64_e32 v[52:53], v[0:1]
	v_mov_b64_e32 v[54:55], v[0:1]
	v_mov_b64_e32 v[56:57], v[0:1]
	v_mov_b64_e32 v[8:9], v[0:1]
	v_mov_b64_e32 v[10:11], v[0:1]
	v_mov_b64_e32 v[12:13], v[0:1]
	v_mov_b64_e32 v[14:15], v[0:1]
	v_mov_b64_e32 v[24:25], v[0:1]
	v_mov_b64_e32 v[26:27], v[0:1]
	v_mov_b64_e32 v[28:29], v[0:1]
	v_mov_b64_e32 v[30:31], v[0:1]
	v_mov_b64_e32 v[42:43], v[0:1]
	v_mov_b64_e32 v[44:45], v[0:1]
	v_mov_b64_e32 v[46:47], v[0:1]
	v_mov_b64_e32 v[48:49], v[0:1]
	v_mov_b64_e32 v[58:59], v[0:1]
	v_mov_b64_e32 v[60:61], v[0:1]
	v_mov_b64_e32 v[62:63], v[0:1]
	v_mov_b64_e32 v[64:65], v[0:1]
	v_mov_b64_e32 v[66:67], v[0:1]
	v_mov_b64_e32 v[68:69], v[0:1]
	v_mov_b64_e32 v[70:71], v[0:1]
	v_mov_b64_e32 v[72:73], v[0:1]
	v_mov_b64_e32 v[82:83], v[0:1]
	v_mov_b64_e32 v[84:85], v[0:1]
	v_mov_b64_e32 v[86:87], v[0:1]
	v_mov_b64_e32 v[88:89], v[0:1]
	s_waitcnt vmcnt(0)
	v_mov_b64_e32 v[98:99], v[0:1]
	v_mov_b64_e32 v[100:101], v[0:1]
	v_mov_b64_e32 v[102:103], v[0:1]
	v_mov_b64_e32 v[104:105], v[0:1]
	v_mov_b64_e32 v[114:115], v[0:1]
	v_mov_b64_e32 v[116:117], v[0:1]
	v_mov_b64_e32 v[118:119], v[0:1]
	v_mov_b64_e32 v[120:121], v[0:1]
	v_mov_b64_e32 v[74:75], v[0:1]
	v_mov_b64_e32 v[76:77], v[0:1]
	v_mov_b64_e32 v[78:79], v[0:1]
	v_mov_b64_e32 v[80:81], v[0:1]
	v_mov_b64_e32 v[90:91], v[0:1]
	v_mov_b64_e32 v[92:93], v[0:1]
	v_mov_b64_e32 v[94:95], v[0:1]
	v_mov_b64_e32 v[96:97], v[0:1]
	v_mov_b64_e32 v[106:107], v[0:1]
	v_mov_b64_e32 v[108:109], v[0:1]
	v_mov_b64_e32 v[110:111], v[0:1]
	v_mov_b64_e32 v[112:113], v[0:1]
	v_mov_b64_e32 v[122:123], v[0:1]
	v_mov_b64_e32 v[124:125], v[0:1]
	v_mov_b64_e32 v[126:127], v[0:1]
	v_mov_b64_e32 v[128:129], v[0:1]
	s_mov_b32 s44, 0x3a800000
	s_cmpk_lt_u32 s69, 0x100
	s_cbranch_scc1 .Lgprio_b
	s_setprio 1
.Lgprio_b:
.LBB0_293:
	s_add_u32 s34, s30, 0xfffc0080
	s_addc_u32 s35, s31, -1
	s_add_i32 s54, 0, 0x10000
	v_add_u32_e32 v150, s54, v181
	ds_read_b128 v[138:141], v150
	ds_read_b128 v[142:145], v150 offset:1024
	ds_read_b128 v[146:149], v150 offset:2048
	ds_read_b128 v[150:153], v150 offset:3072
	s_cmp_eq_u32 s51, 12
	s_cselect_b32 s37, s21, s35
	s_cselect_b32 s36, s29, s34
	s_cselect_b32 s35, s19, s50
	s_cselect_b32 s34, s33, s49
	v_lshl_add_u64 v[178:179], s[30:31], 0, v[134:135]
	s_add_i32 m0, s64, 0xc000
	ds_read_b128 v[154:157], v190
	ds_read_b128 v[158:161], v190 offset:1024
	ds_read_b128 v[162:165], v190 offset:2048
	ds_read_b128 v[166:169], v190 offset:3072
	ds_read_b128 v[170:173], v190 offset:4096
	ds_read_b128 v[202:205], v190 offset:5120
	ds_read_b128 v[206:209], v190 offset:6144
	ds_read_b128 v[210:213], v190 offset:7168
	global_load_lds_dwordx4 v[178:179], off
	v_lshl_add_u64 v[178:179], s[30:31], 0, v[136:137]
	s_add_i32 m0, s64, 0xe000
	s_nop 0
	global_load_lds_dwordx4 v[178:179], off
	s_waitcnt lgkmcnt(8)
	s_barrier
	s_waitcnt lgkmcnt(0)
	s_waitcnt lgkmcnt(0)
	v_mfma_f32_16x16x32_f16 v[126:129], v[138:141], v[154:157], v[126:129]
	v_mfma_f32_16x16x32_f16 v[122:125], v[146:149], v[154:157], v[122:125]
	v_mfma_f32_16x16x32_f16 v[110:113], v[138:141], v[162:165], v[110:113]
	v_mfma_f32_16x16x32_f16 v[106:109], v[146:149], v[162:165], v[106:109]
	v_mfma_f32_16x16x32_f16 v[94:97], v[138:141], v[170:173], v[94:97]
	v_mfma_f32_16x16x32_f16 v[90:93], v[146:149], v[170:173], v[90:93]
	v_mfma_f32_16x16x32_f16 v[78:81], v[138:141], v[206:209], v[78:81]
	v_mfma_f32_16x16x32_f16 v[74:77], v[146:149], v[206:209], v[74:77]
	v_mfma_f32_16x16x32_f16 v[126:129], v[142:145], v[158:161], v[126:129]
	v_mfma_f32_16x16x32_f16 v[122:125], v[150:153], v[158:161], v[122:125]
	v_mfma_f32_16x16x32_f16 v[110:113], v[142:145], v[166:169], v[110:113]
	v_mfma_f32_16x16x32_f16 v[106:109], v[150:153], v[166:169], v[106:109]
	v_mfma_f32_16x16x32_f16 v[94:97], v[142:145], v[202:205], v[94:97]
	v_mfma_f32_16x16x32_f16 v[90:93], v[150:153], v[202:205], v[90:93]
	v_mfma_f32_16x16x32_f16 v[78:81], v[142:145], v[210:213], v[78:81]
	v_mfma_f32_16x16x32_f16 v[74:77], v[150:153], v[210:213], v[74:77]
	s_barrier
	s_add_i32 s57, 0, 0x14000
	s_add_i32 s54, s54, s62
	v_add_u32_e32 v174, s57, v181
	v_lshl_add_u64 v[178:179], s[34:35], 0, v[130:131]
	s_mov_b32 m0, s54
	ds_read_b128 v[214:217], v174
	ds_read_b128 v[218:221], v174 offset:1024
	ds_read_b128 v[222:225], v174 offset:2048
	ds_read_b128 v[244:247], v174 offset:3072
	global_load_lds_dwordx4 v[178:179], off
	v_lshl_add_u64 v[192:193], s[34:35], 0, v[132:133]
	s_add_i32 m0, s54, 0x2000
	s_nop 0
	global_load_lds_dwordx4 v[192:193], off
	s_barrier
; #define PG8_STAGE(bufoff, gbase, voff) do { _Pragma("unroll") for (int _i = 0; _i < 2; ++_i) \
;     __builtin_amdgcn_global_load_lds((const unsigned*)((const char*)(gbase) + (voff)[_i]), (LAS unsigned*)(lds + (bufoff) + ldsw + _i * 8192), 16, 0, 0); } while (0)
; #define PG8_LDA(dst, b, h) do { _Pragma("unroll") for (int m = 0; m < 4; ++m) _Pragma("unroll") for (int k = 0; k < 2; ++k) dst[m][k] = *(const LAS bf16x8*)(lds + PG8_SA(b, h) + aoff + m * 2048 + k * 1024); } while (0)
; #define PG8_LDB(dst, b, h) do { _Pragma("unroll") for (int n = 0; n < 2; ++n) _Pragma("unroll") for (int k = 0; k < 2; ++k) dst[n][k] = *(const LAS bf16x8*)(lds + PG8_SB(b, h) + boff + n * 2048 + k * 1024); } while (0)
; #define PG8_WAIT_V(n) asm volatile("s_waitcnt vmcnt(" #n ")" ::: "memory")
; #define PG8_WAIT_L(n) asm volatile("s_waitcnt lgkmcnt(" #n ")" ::: "memory")
; #define PG8_BAR __builtin_amdgcn_s_barrier()
; #define PG8_SCHED __builtin_amdgcn_sched_barrier(0)
; template <class Epi>
; DI void gemm_phase(int wv, LAS unsigned char* lds, const Gemm g, const StaticOrder& S, const Epi& E) {
;     ...
;       PG8_BAR; PG8_WAIT_L(0); PG8_MMA(0, 1, At, B1); PG8_BAR;
;       PG8_LDA(At, 0, 1); PG8_STAGE(PG8_SA(0, 0), a2, voffA);
;       PG8_BAR; PG8_WAIT_L(0); PG8_MMA(1, 0, At, B0); PG8_BAR; PG8_SCHED;
;       PG8_STAGE(PG8_SB(0, 1), b2 + hstep, voffA);
;       PG8_WAIT_V(6); PG8_BAR; PG8_MMA(1, 1, At, B1); PG8_BAR;
;       PG8_LDB(B0, 1, 0); PG8_SCHED; PG8_LDA(At, 1, 0); PG8_STAGE(PG8_SA(0, 1), a2 + hstep, voffA);
;       PG8_WAIT_L(8); PG8_BAR; PG8_WAIT_L(0); PG8_MMA(0, 0, At, B0); PG8_BAR; PG8_SCHED;
	s_waitcnt lgkmcnt(0)
	s_waitcnt lgkmcnt(0)
	v_mfma_f32_16x16x32_f16 v[118:121], v[214:217], v[154:157], v[118:121]
	v_mfma_f32_16x16x32_f16 v[114:117], v[222:225], v[154:157], v[114:117]
	v_mfma_f32_16x16x32_f16 v[102:105], v[214:217], v[162:165], v[102:105]
	v_mfma_f32_16x16x32_f16 v[98:101], v[222:225], v[162:165], v[98:101]
	v_mfma_f32_16x16x32_f16 v[86:89], v[214:217], v[170:173], v[86:89]
	v_mfma_f32_16x16x32_f16 v[82:85], v[222:225], v[170:173], v[82:85]
	v_mfma_f32_16x16x32_f16 v[70:73], v[214:217], v[206:209], v[70:73]
	v_mfma_f32_16x16x32_f16 v[66:69], v[222:225], v[206:209], v[66:69]
	v_mfma_f32_16x16x32_f16 v[118:121], v[218:221], v[158:161], v[118:121]
	v_mfma_f32_16x16x32_f16 v[114:117], v[244:247], v[158:161], v[114:117]
	v_mfma_f32_16x16x32_f16 v[102:105], v[218:221], v[166:169], v[102:105]
	v_mfma_f32_16x16x32_f16 v[98:101], v[244:247], v[166:169], v[98:101]
	v_mfma_f32_16x16x32_f16 v[86:89], v[218:221], v[202:205], v[86:89]
	v_mfma_f32_16x16x32_f16 v[82:85], v[244:247], v[202:205], v[82:85]
	v_mfma_f32_16x16x32_f16 v[70:73], v[218:221], v[210:213], v[70:73]
	v_mfma_f32_16x16x32_f16 v[66:69], v[244:247], v[210:213], v[66:69]
	s_mov_b32 m0, s64
	v_lshl_add_u64 v[226:227], s[36:37], 0, v[130:131]
	s_barrier
	ds_read_b128 v[154:157], v190 offset:16384
	ds_read_b128 v[158:161], v190 offset:17408
	ds_read_b128 v[162:165], v190 offset:18432
	ds_read_b128 v[166:169], v190 offset:19456
	ds_read_b128 v[170:173], v190 offset:20480
	ds_read_b128 v[202:205], v190 offset:21504
	ds_read_b128 v[206:209], v190 offset:22528
	ds_read_b128 v[210:213], v190 offset:23552
	global_load_lds_dwordx4 v[226:227], off
	v_lshl_add_u64 v[230:231], s[36:37], 0, v[132:133]
	s_mov_b32 m0, s84
	s_nop 0
	global_load_lds_dwordx4 v[230:231], off
	s_barrier
	s_waitcnt lgkmcnt(0)
	s_waitcnt lgkmcnt(0)
	v_mfma_f32_16x16x32_f16 v[62:65], v[138:141], v[154:157], v[62:65]
	v_mfma_f32_16x16x32_f16 v[58:61], v[146:149], v[154:157], v[58:61]
	v_mfma_f32_16x16x32_f16 v[46:49], v[138:141], v[162:165], v[46:49]
	v_mfma_f32_16x16x32_f16 v[42:45], v[146:149], v[162:165], v[42:45]
	v_mfma_f32_16x16x32_f16 v[28:31], v[138:141], v[170:173], v[28:31]
	v_mfma_f32_16x16x32_f16 v[24:27], v[146:149], v[170:173], v[24:27]
	v_mfma_f32_16x16x32_f16 v[12:15], v[138:141], v[206:209], v[12:15]
	v_mfma_f32_16x16x32_f16 v[8:11], v[146:149], v[206:209], v[8:11]
	v_mfma_f32_16x16x32_f16 v[62:65], v[142:145], v[158:161], v[62:65]
	v_mfma_f32_16x16x32_f16 v[58:61], v[150:153], v[158:161], v[58:61]
	v_mfma_f32_16x16x32_f16 v[46:49], v[142:145], v[166:169], v[46:49]
	v_mfma_f32_16x16x32_f16 v[42:45], v[150:153], v[166:169], v[42:45]
	v_mfma_f32_16x16x32_f16 v[28:31], v[142:145], v[202:205], v[28:31]
	v_mfma_f32_16x16x32_f16 v[24:27], v[150:153], v[202:205], v[24:27]
	v_mfma_f32_16x16x32_f16 v[12:15], v[142:145], v[210:213], v[12:15]
	v_mfma_f32_16x16x32_f16 v[8:11], v[150:153], v[210:213], v[8:11]
	s_barrier
	s_add_u32 s70, s34, 0x40000
	s_addc_u32 s71, s35, 0
	s_add_i32 s54, s57, s62
	v_lshl_add_u64 v[138:139], s[70:71], 0, v[130:131]
	s_mov_b32 m0, s54
	s_nop 0
	global_load_lds_dwordx4 v[138:139], off
	v_lshl_add_u64 v[138:139], s[70:71], 0, v[132:133]
	s_add_i32 m0, s54, 0x2000
	s_nop 0
	global_load_lds_dwordx4 v[138:139], off
	s_waitcnt vmcnt(6)
	s_barrier
	v_mfma_f32_16x16x32_f16 v[54:57], v[214:217], v[154:157], v[54:57]
	v_mfma_f32_16x16x32_f16 v[50:53], v[222:225], v[154:157], v[50:53]
	v_mfma_f32_16x16x32_f16 v[38:41], v[214:217], v[162:165], v[38:41]
	v_mfma_f32_16x16x32_f16 v[34:37], v[222:225], v[162:165], v[34:37]
	v_mfma_f32_16x16x32_f16 v[20:23], v[214:217], v[170:173], v[20:23]
	v_mfma_f32_16x16x32_f16 v[16:19], v[222:225], v[170:173], v[16:19]
	v_mfma_f32_16x16x32_f16 v[4:7], v[214:217], v[206:209], v[4:7]
	v_mfma_f32_16x16x32_f16 v[0:3], v[222:225], v[206:209], v[0:3]
	v_mfma_f32_16x16x32_f16 v[54:57], v[218:221], v[158:161], v[54:57]
	v_mfma_f32_16x16x32_f16 v[50:53], v[244:247], v[158:161], v[50:53]
	v_mfma_f32_16x16x32_f16 v[38:41], v[218:221], v[166:169], v[38:41]
	v_mfma_f32_16x16x32_f16 v[34:37], v[244:247], v[166:169], v[34:37]
	v_mfma_f32_16x16x32_f16 v[20:23], v[218:221], v[202:205], v[20:23]
	v_mfma_f32_16x16x32_f16 v[16:19], v[244:247], v[202:205], v[16:19]
	v_mfma_f32_16x16x32_f16 v[4:7], v[218:221], v[210:213], v[4:7]
	v_mfma_f32_16x16x32_f16 v[0:3], v[244:247], v[210:213], v[0:3]
	s_add_i32 s54, 0, 0x18000
	v_add_u32_e32 v150, s54, v181
	s_barrier
	ds_read_b128 v[138:141], v150
	ds_read_b128 v[142:145], v150 offset:1024
	ds_read_b128 v[146:149], v150 offset:2048
	ds_read_b128 v[150:153], v150 offset:3072
	s_add_u32 s36, s36, 0x40000
	s_addc_u32 s37, s37, 0
	s_mov_b32 m0, s90
	v_lshl_add_u64 v[214:215], s[36:37], 0, v[130:131]
	ds_read_b128 v[154:157], v190 offset:32768
	ds_read_b128 v[158:161], v190 offset:33792
	ds_read_b128 v[162:165], v190 offset:34816
	ds_read_b128 v[166:169], v190 offset:35840
	ds_read_b128 v[170:173], v190 offset:36864
	ds_read_b128 v[202:205], v190 offset:37888
	ds_read_b128 v[206:209], v190 offset:38912
	ds_read_b128 v[210:213], v190 offset:39936
	global_load_lds_dwordx4 v[214:215], off
	v_lshl_add_u64 v[214:215], s[36:37], 0, v[132:133]
	s_mov_b32 m0, s91
	s_nop 0
	global_load_lds_dwordx4 v[214:215], off
	s_waitcnt lgkmcnt(8)
	s_barrier
; #define PG8_STAGE(bufoff, gbase, voff) do { _Pragma("unroll") for (int _i = 0; _i < 2; ++_i) \
;     __builtin_amdgcn_global_load_lds((const unsigned*)((const char*)(gbase) + (voff)[_i]), (LAS unsigned*)(lds + (bufoff) + ldsw + _i * 8192), 16, 0, 0); } while (0)
; #define PG8_LDA(dst, b, h) do { _Pragma("unroll") for (int m = 0; m < 4; ++m) _Pragma("unroll") for (int k = 0; k < 2; ++k) dst[m][k] = *(const LAS bf16x8*)(lds + PG8_SA(b, h) + aoff + m * 2048 + k * 1024); } while (0)
; #define PG8_LDB(dst, b, h) do { _Pragma("unroll") for (int n = 0; n < 2; ++n) _Pragma("unroll") for (int k = 0; k < 2; ++k) dst[n][k] = *(const LAS bf16x8*)(lds + PG8_SB(b, h) + boff + n * 2048 + k * 1024); } while (0)
; #define PG8_WAIT_V(n) asm volatile("s_waitcnt vmcnt(" #n ")" ::: "memory")
; #define PG8_WAIT_L(n) asm volatile("s_waitcnt lgkmcnt(" #n ")" ::: "memory")
; #define PG8_BAR __builtin_amdgcn_s_barrier()
; #define PG8_SCHED __builtin_amdgcn_sched_barrier(0)
; template <class Epi>
; DI void gemm_phase(int wv, LAS unsigned char* lds, const Gemm g, const StaticOrder& S, const Epi& E) {
;     ...
;       PG8_WAIT_L(8); PG8_BAR; PG8_WAIT_L(0); PG8_MMA(0, 0, At, B0); PG8_BAR; PG8_SCHED;
;       PG8_LDB(B1, 1, 1); PG8_STAGE(PG8_SB(1, 0), b3, voffA);
;       PG8_BAR; PG8_WAIT_L(0); PG8_MMA(0, 1, At, B1); PG8_BAR;
;       PG8_LDA(At, 1, 1); PG8_STAGE(PG8_SA(1, 0), a3, voffA);
;       PG8_BAR; PG8_WAIT_L(0); PG8_MMA(1, 0, At, B0); PG8_BAR; PG8_SCHED;
;       PG8_STAGE(PG8_SB(1, 1), b3 + hstep, voffA);
;       PG8_WAIT_V(6); PG8_BAR; PG8_MMA(1, 1, At, B1); PG8_BAR;
	s_waitcnt lgkmcnt(0)
	s_waitcnt lgkmcnt(0)
	v_mfma_f32_16x16x32_f16 v[126:129], v[138:141], v[154:157], v[126:129]
	v_mfma_f32_16x16x32_f16 v[122:125], v[146:149], v[154:157], v[122:125]
	v_mfma_f32_16x16x32_f16 v[110:113], v[138:141], v[162:165], v[110:113]
	v_mfma_f32_16x16x32_f16 v[106:109], v[146:149], v[162:165], v[106:109]
	v_mfma_f32_16x16x32_f16 v[94:97], v[138:141], v[170:173], v[94:97]
	v_mfma_f32_16x16x32_f16 v[90:93], v[146:149], v[170:173], v[90:93]
	v_mfma_f32_16x16x32_f16 v[78:81], v[138:141], v[206:209], v[78:81]
	v_mfma_f32_16x16x32_f16 v[74:77], v[146:149], v[206:209], v[74:77]
	v_mfma_f32_16x16x32_f16 v[126:129], v[142:145], v[158:161], v[126:129]
	v_mfma_f32_16x16x32_f16 v[122:125], v[150:153], v[158:161], v[122:125]
	v_mfma_f32_16x16x32_f16 v[110:113], v[142:145], v[166:169], v[110:113]
	v_mfma_f32_16x16x32_f16 v[106:109], v[150:153], v[166:169], v[106:109]
	v_mfma_f32_16x16x32_f16 v[94:97], v[142:145], v[202:205], v[94:97]
	v_mfma_f32_16x16x32_f16 v[90:93], v[150:153], v[202:205], v[90:93]
	v_mfma_f32_16x16x32_f16 v[78:81], v[142:145], v[210:213], v[78:81]
	v_mfma_f32_16x16x32_f16 v[74:77], v[150:153], v[210:213], v[74:77]
	s_barrier
	s_add_i32 s36, 0, 0x1c000
	s_add_i32 s37, s54, s62
	v_add_u32_e32 v174, s36, v181
	v_lshl_add_u64 v[178:179], v[178:179], 0, s[2:3]
	s_mov_b32 m0, s37
	ds_read_b128 v[214:217], v174
	ds_read_b128 v[218:221], v174 offset:1024
	ds_read_b128 v[222:225], v174 offset:2048
	ds_read_b128 v[244:247], v174 offset:3072
	global_load_lds_dwordx4 v[178:179], off
	v_lshl_add_u64 v[178:179], v[192:193], 0, s[2:3]
	s_add_i32 m0, s37, 0x2000
	s_nop 0
	global_load_lds_dwordx4 v[178:179], off
	s_barrier
	s_waitcnt lgkmcnt(0)
	s_waitcnt lgkmcnt(0)
	v_mfma_f32_16x16x32_f16 v[118:121], v[214:217], v[154:157], v[118:121]
	v_mfma_f32_16x16x32_f16 v[114:117], v[222:225], v[154:157], v[114:117]
	v_mfma_f32_16x16x32_f16 v[102:105], v[214:217], v[162:165], v[102:105]
	v_mfma_f32_16x16x32_f16 v[98:101], v[222:225], v[162:165], v[98:101]
	v_mfma_f32_16x16x32_f16 v[86:89], v[214:217], v[170:173], v[86:89]
	v_mfma_f32_16x16x32_f16 v[82:85], v[222:225], v[170:173], v[82:85]
	v_mfma_f32_16x16x32_f16 v[70:73], v[214:217], v[206:209], v[70:73]
	v_mfma_f32_16x16x32_f16 v[66:69], v[222:225], v[206:209], v[66:69]
	v_mfma_f32_16x16x32_f16 v[118:121], v[218:221], v[158:161], v[118:121]
	v_mfma_f32_16x16x32_f16 v[114:117], v[244:247], v[158:161], v[114:117]
	v_mfma_f32_16x16x32_f16 v[102:105], v[218:221], v[166:169], v[102:105]
	v_mfma_f32_16x16x32_f16 v[98:101], v[244:247], v[166:169], v[98:101]
	v_mfma_f32_16x16x32_f16 v[86:89], v[218:221], v[202:205], v[86:89]
	v_mfma_f32_16x16x32_f16 v[82:85], v[244:247], v[202:205], v[82:85]
	v_mfma_f32_16x16x32_f16 v[70:73], v[218:221], v[210:213], v[70:73]
	v_mfma_f32_16x16x32_f16 v[66:69], v[244:247], v[210:213], v[66:69]
	s_mov_b32 m0, s41
	v_lshl_add_u64 v[178:179], v[226:227], 0, s[2:3]
	s_barrier
	ds_read_b128 v[154:157], v190 offset:49152
	ds_read_b128 v[158:161], v190 offset:50176
	ds_read_b128 v[162:165], v190 offset:51200
	ds_read_b128 v[166:169], v190 offset:52224
	ds_read_b128 v[170:173], v190 offset:53248
	ds_read_b128 v[202:205], v190 offset:54272
	ds_read_b128 v[206:209], v190 offset:55296
	ds_read_b128 v[210:213], v190 offset:56320
	global_load_lds_dwordx4 v[178:179], off
	v_lshl_add_u64 v[178:179], v[230:231], 0, s[2:3]
	s_mov_b32 m0, s42
	s_nop 0
	global_load_lds_dwordx4 v[178:179], off
	s_barrier
	s_waitcnt lgkmcnt(0)
	s_waitcnt lgkmcnt(0)
	v_mfma_f32_16x16x32_f16 v[62:65], v[138:141], v[154:157], v[62:65]
	v_mfma_f32_16x16x32_f16 v[58:61], v[146:149], v[154:157], v[58:61]
	v_mfma_f32_16x16x32_f16 v[46:49], v[138:141], v[162:165], v[46:49]
	v_mfma_f32_16x16x32_f16 v[42:45], v[146:149], v[162:165], v[42:45]
	v_mfma_f32_16x16x32_f16 v[28:31], v[138:141], v[170:173], v[28:31]
	v_mfma_f32_16x16x32_f16 v[24:27], v[146:149], v[170:173], v[24:27]
	v_mfma_f32_16x16x32_f16 v[12:15], v[138:141], v[206:209], v[12:15]
	v_mfma_f32_16x16x32_f16 v[8:11], v[146:149], v[206:209], v[8:11]
	v_mfma_f32_16x16x32_f16 v[62:65], v[142:145], v[158:161], v[62:65]
	v_mfma_f32_16x16x32_f16 v[58:61], v[150:153], v[158:161], v[58:61]
	v_mfma_f32_16x16x32_f16 v[46:49], v[142:145], v[166:169], v[46:49]
	v_mfma_f32_16x16x32_f16 v[42:45], v[150:153], v[166:169], v[42:45]
	v_mfma_f32_16x16x32_f16 v[28:31], v[142:145], v[202:205], v[28:31]
	v_mfma_f32_16x16x32_f16 v[24:27], v[150:153], v[202:205], v[24:27]
	v_mfma_f32_16x16x32_f16 v[12:15], v[142:145], v[210:213], v[12:15]
	v_mfma_f32_16x16x32_f16 v[8:11], v[150:153], v[210:213], v[8:11]
	s_barrier
	s_add_u32 s34, s34, 0x40080
	s_addc_u32 s35, s35, 0
	s_add_i32 s36, s36, s62
	v_lshl_add_u64 v[138:139], s[34:35], 0, v[130:131]
	s_mov_b32 m0, s36
	s_nop 0
	global_load_lds_dwordx4 v[138:139], off
	v_lshl_add_u64 v[138:139], s[34:35], 0, v[132:133]
	s_add_i32 m0, s36, 0x2000
	s_nop 0
	global_load_lds_dwordx4 v[138:139], off
	s_waitcnt vmcnt(6)
	s_barrier
	v_mfma_f32_16x16x32_f16 v[54:57], v[214:217], v[154:157], v[54:57]
	v_mfma_f32_16x16x32_f16 v[50:53], v[222:225], v[154:157], v[50:53]
	v_mfma_f32_16x16x32_f16 v[38:41], v[214:217], v[162:165], v[38:41]
	v_mfma_f32_16x16x32_f16 v[34:37], v[222:225], v[162:165], v[34:37]
	v_mfma_f32_16x16x32_f16 v[20:23], v[214:217], v[170:173], v[20:23]
	v_mfma_f32_16x16x32_f16 v[16:19], v[222:225], v[170:173], v[16:19]
	v_mfma_f32_16x16x32_f16 v[4:7], v[214:217], v[206:209], v[4:7]
	v_mfma_f32_16x16x32_f16 v[0:3], v[222:225], v[206:209], v[0:3]
	v_mfma_f32_16x16x32_f16 v[54:57], v[218:221], v[158:161], v[54:57]
	v_mfma_f32_16x16x32_f16 v[50:53], v[244:247], v[158:161], v[50:53]
	v_mfma_f32_16x16x32_f16 v[38:41], v[218:221], v[166:169], v[38:41]
	v_mfma_f32_16x16x32_f16 v[34:37], v[244:247], v[166:169], v[34:37]
	v_mfma_f32_16x16x32_f16 v[20:23], v[218:221], v[202:205], v[20:23]
	v_mfma_f32_16x16x32_f16 v[16:19], v[244:247], v[202:205], v[16:19]
	v_mfma_f32_16x16x32_f16 v[4:7], v[218:221], v[210:213], v[4:7]
	v_mfma_f32_16x16x32_f16 v[0:3], v[244:247], v[210:213], v[0:3]
	s_add_i32 s51, s51, 2
	s_add_u32 s30, s30, 0x100
	s_addc_u32 s31, s31, 0
	s_add_u32 s49, s49, 0x100
	s_addc_u32 s50, s50, 0
	s_cmp_gt_u32 s51, 13
	s_barrier
; #define LAS __attribute__((address_space(3)))
; DI unsigned pk2(float a, float b) { typedef __bf16 bf2 __attribute__((ext_vector_type(2))); bf2 v; v[0] = (__bf16)a; v[1] = (__bf16)b; return __builtin_bit_cast(unsigned, v); }
;   template <int SECT>
;   DI void body(const f32x4 (&acc)[2][2][4][2], const pg8::Unit& u, int wr, int wc, int fr, int fq, LAS unsigned char* lds, int ui, int wid) const {
;     const int col0 = u.pn * 256 + wc * 32 + 8 * fq;
;     int fq_ = fq, fr_ = fr; asm volatile("" : "+v"(fq_), "+v"(fr_));
;     const LAS float* cl = (const LAS float*)(lds + 139264 + (ui & 1) * 3072) + wc * 32 + 8 * fq_;
;     const LAS float* sl = (const LAS float*)(lds + 131072 + wid * 1024);
; #pragma unroll
;     for (int ai = 0; ai < 2; ++ai)
; #pragma unroll
;       for (int m = 0; m < 4; ++m) {
;         const int row = u.pm * 256 + ai * 128 + wr * 64 + m * 16 + fr; float a, bb;
;         { typedef float f32x2_ __attribute__((ext_vector_type(2))); const f32x2_ sv = *(const LAS f32x2_*)(sl + ai * 128 + (m * 16 + fr_) * 2);
;           const float mu = sv.x * (1.0f / 1024.0f), var = fmaxf(sv.y * (1.0f / 1024.0f) - mu * mu, 0.f), rstd = rsqrtf(var + 1e-5f); a = rstd; bb = -rstd * mu; }
; #pragma unroll
;         for (int bj = 0; bj < 2; ++bj) {
;           const int col = col0 + bj * 128;
;           f32x4 v[2];
; #pragma unroll
;           for (int n = 0; n < 2; ++n) v[n] = acc[ai][bj][m][n] * a + (*(const LAS f32x4*)(cl + bj * 128 + 4 * n)) * bb + *(const LAS f32x4*)(cl + 256 + bj * 128 + 4 * n);
;           if (SECT < 0) { u32x4 w; w[0] = pk2(v[0][0], v[0][1]); w[1] = pk2(v[0][2], v[0][3]); w[2] = pk2(v[1][0], v[1][1]); w[3] = pk2(v[1][2], v[1][3]); *(u32x4*)(h + (size_t)row * ld + col) = w; }
	s_cbranch_scc0 .LBB0_293
	s_lshl_b32 s21, s26, 8
	s_bitcmp1_b32 s27, 0
	s_cselect_b32 s19, 0xc00, 0
	s_lshl_b32 s27, s28, 8
	v_readlane_b32 s30, v255, 41
	v_add_u32_e32 v170, s27, v180
	v_add_u32_e32 v168, s27, v182
	v_add_u32_e32 v166, s27, v183
	v_add_u32_e32 v162, s27, v184
	v_add_u32_e32 v160, s27, v185
	v_add_u32_e32 v156, s27, v186
	v_add_u32_e32 v152, s27, v187
	v_add_u32_e32 v150, s27, v188
	v_readlane_b32 s31, v255, 42
	s_add_i32 s19, s39, s19
	v_ashrrev_i32_e32 v171, 31, v170
	v_ashrrev_i32_e32 v169, 31, v168
	v_ashrrev_i32_e32 v167, 31, v166
	v_ashrrev_i32_e32 v163, 31, v162
	v_ashrrev_i32_e32 v161, 31, v160
	v_ashrrev_i32_e32 v157, 31, v156
	v_ashrrev_i32_e32 v153, 31, v152
	v_ashrrev_i32_e32 v151, 31, v150
	v_or_b32_e32 v146, s21, v189
	v_mov_b32_e32 v147, v32
	s_mov_b64 s[28:29], -1
	s_and_b64 vcc, exec, s[30:31]
	s_cbranch_vccz .LBB0_296
	v_mov_b32_e32 v140, v177
	v_mov_b32_e32 v141, v175
	s_mov_b32 s27, 0x800000
	v_lshl_add_u32 v141, v141, 3, s65
	ds_read_b64 v[142:143], v141
	v_lshl_add_u32 v140, v140, 5, s19
	v_readlane_b32 s30, v255, 45
	v_ashrrev_i32_e32 v139, 31, v146
	v_mov_b32_e32 v138, v146
	s_waitcnt lgkmcnt(0)
	v_pk_mul_f32 v[142:143], v[142:143], s[44:45] op_sel_hi:[1,0]
	v_lshlrev_b64 v[138:139], 1, v[138:139]
	v_fma_f32 v143, -v142, v142, v143
	v_max_f32_e32 v143, 0, v143
	v_add_f32_e32 v143, 0x3727c5ac, v143
	v_cmp_gt_f32_e32 vcc, s27, v143
	v_mul_f32_e32 v144, 0x4b800000, v143
	s_nop 0
	v_cndmask_b32_e32 v143, v143, v144, vcc
	v_rsq_f32_e32 v143, v143
	s_nop 0
	v_mul_f32_e32 v144, 0x45800000, v143
	v_cndmask_b32_e32 v148, v143, v144, vcc
	v_mul_f32_e64 v154, v142, -v148
	ds_read_b128 v[142:145], v140
	ds_read_b128 v[202:205], v140 offset:16
	s_waitcnt lgkmcnt(0)
	v_pk_mul_f32 v[144:145], v[144:145], v[154:155] op_sel_hi:[1,0]
	v_pk_mul_f32 v[142:143], v[142:143], v[154:155] op_sel_hi:[1,0]
	v_pk_fma_f32 v[164:165], v[128:129], v[148:149], v[144:145] op_sel_hi:[1,0,1]
	v_pk_fma_f32 v[158:159], v[126:127], v[148:149], v[142:143] op_sel_hi:[1,0,1]
	ds_read_b128 v[142:145], v140 offset:1024
	s_waitcnt lgkmcnt(0)
	v_pk_add_f32 v[164:165], v[144:145], v[164:165]
	v_pk_add_f32 v[158:159], v[142:143], v[158:159]
	v_pk_mul_f32 v[142:143], v[204:205], v[154:155] op_sel_hi:[1,0]
	v_pk_mul_f32 v[144:145], v[202:203], v[154:155] op_sel_hi:[1,0]
	v_pk_fma_f32 v[178:179], v[124:125], v[148:149], v[142:143] op_sel_hi:[1,0,1]
	v_pk_fma_f32 v[172:173], v[122:123], v[148:149], v[144:145] op_sel_hi:[1,0,1]
	ds_read_b128 v[142:145], v140 offset:1040
	s_waitcnt lgkmcnt(0)
	v_pk_add_f32 v[178:179], v[144:145], v[178:179]
	v_pk_add_f32 v[144:145], v[142:143], v[172:173]
	v_cvt_pk_bf16_f32 v142, v158, v159
	v_mad_i64_i32 v[158:159], s[28:29], v170, s30, 0
	v_lshl_add_u64 v[158:159], v[158:159], 1, s[10:11]
	v_cvt_pk_bf16_f32 v143, v164, v165
	v_cvt_pk_bf16_f32 v144, v144, v145
	v_cvt_pk_bf16_f32 v145, v178, v179
	v_lshl_add_u64 v[158:159], v[158:159], 0, v[138:139]
	global_store_dwordx4 v[158:159], v[142:145], off
	ds_read_b128 v[142:145], v140 offset:512
	s_waitcnt lgkmcnt(0)
	v_pk_mul_f32 v[144:145], v[144:145], v[154:155] op_sel_hi:[1,0]
	v_pk_mul_f32 v[142:143], v[142:143], v[154:155] op_sel_hi:[1,0]
	v_pk_fma_f32 v[172:173], v[120:121], v[148:149], v[144:145] op_sel_hi:[1,0,1]
	v_pk_fma_f32 v[164:165], v[118:119], v[148:149], v[142:143] op_sel_hi:[1,0,1]
	ds_read_b128 v[142:145], v140 offset:1536
	s_waitcnt lgkmcnt(0)
	v_pk_add_f32 v[172:173], v[144:145], v[172:173]
	v_pk_add_f32 v[164:165], v[142:143], v[164:165]
	ds_read_b128 v[142:145], v140 offset:528
	s_waitcnt lgkmcnt(0)
	v_pk_mul_f32 v[144:145], v[144:145], v[154:155] op_sel_hi:[1,0]
	v_pk_mul_f32 v[142:143], v[142:143], v[154:155] op_sel_hi:[1,0]
	s_nop 0
	v_pk_fma_f32 v[154:155], v[114:115], v[148:149], v[142:143] op_sel_hi:[1,0,1]
	v_pk_fma_f32 v[148:149], v[116:117], v[148:149], v[144:145] op_sel_hi:[1,0,1]
	ds_read_b128 v[142:145], v140 offset:1552
	s_waitcnt lgkmcnt(0)
	v_pk_add_f32 v[148:149], v[144:145], v[148:149]
	v_pk_add_f32 v[144:145], v[142:143], v[154:155]
	v_cvt_pk_bf16_f32 v142, v164, v165
	v_cvt_pk_bf16_f32 v143, v172, v173
	v_cvt_pk_bf16_f32 v144, v144, v145
	v_cvt_pk_bf16_f32 v145, v148, v149
	global_store_dwordx4 v[158:159], v[142:145], off offset:256
	ds_read_b64 v[142:143], v141 offset:128
	s_waitcnt lgkmcnt(0)
	v_pk_mul_f32 v[142:143], v[142:143], s[44:45] op_sel_hi:[1,0]
	s_nop 0
	v_fma_f32 v143, -v142, v142, v143
	v_max_f32_e32 v143, 0, v143
	v_add_f32_e32 v143, 0x3727c5ac, v143
	v_cmp_gt_f32_e32 vcc, s27, v143
	v_mul_f32_e32 v144, 0x4b800000, v143
	s_nop 0
	v_cndmask_b32_e32 v143, v143, v144, vcc
	v_rsq_f32_e32 v143, v143
	s_nop 0
	v_mul_f32_e32 v144, 0x45800000, v143
	v_cndmask_b32_e32 v148, v143, v144, vcc
	v_mul_f32_e64 v154, v142, -v148
	ds_read_b128 v[142:145], v140
	ds_read_b128 v[202:205], v140 offset:16
	s_waitcnt lgkmcnt(0)
	v_pk_mul_f32 v[144:145], v[144:145], v[154:155] op_sel_hi:[1,0]
	v_pk_mul_f32 v[142:143], v[142:143], v[154:155] op_sel_hi:[1,0]
	v_pk_fma_f32 v[164:165], v[112:113], v[148:149], v[144:145] op_sel_hi:[1,0,1]
	v_pk_fma_f32 v[158:159], v[110:111], v[148:149], v[142:143] op_sel_hi:[1,0,1]
	ds_read_b128 v[142:145], v140 offset:1024
	s_waitcnt lgkmcnt(0)
	v_pk_add_f32 v[164:165], v[144:145], v[164:165]
	v_pk_add_f32 v[158:159], v[142:143], v[158:159]
	v_pk_mul_f32 v[142:143], v[204:205], v[154:155] op_sel_hi:[1,0]
	v_pk_mul_f32 v[144:145], v[202:203], v[154:155] op_sel_hi:[1,0]
	v_pk_fma_f32 v[178:179], v[108:109], v[148:149], v[142:143] op_sel_hi:[1,0,1]
	v_pk_fma_f32 v[172:173], v[106:107], v[148:149], v[144:145] op_sel_hi:[1,0,1]
	ds_read_b128 v[142:145], v140 offset:1040
	s_waitcnt lgkmcnt(0)
; #define LAS __attribute__((address_space(3)))
; DI unsigned pk2(float a, float b) { typedef __bf16 bf2 __attribute__((ext_vector_type(2))); bf2 v; v[0] = (__bf16)a; v[1] = (__bf16)b; return __builtin_bit_cast(unsigned, v); }
;   template <int SECT>
;   DI void body(const f32x4 (&acc)[2][2][4][2], const pg8::Unit& u, int wr, int wc, int fr, int fq, LAS unsigned char* lds, int ui, int wid) const {
;     ...
;       for (int m = 0; m < 4; ++m) {
;         const int row = u.pm * 256 + ai * 128 + wr * 64 + m * 16 + fr; float a, bb;
;         { typedef float f32x2_ __attribute__((ext_vector_type(2))); const f32x2_ sv = *(const LAS f32x2_*)(sl + ai * 128 + (m * 16 + fr_) * 2);
;           const float mu = sv.x * (1.0f / 1024.0f), var = fmaxf(sv.y * (1.0f / 1024.0f) - mu * mu, 0.f), rstd = rsqrtf(var + 1e-5f); a = rstd; bb = -rstd * mu; }
; #pragma unroll
;         for (int bj = 0; bj < 2; ++bj) {
;           const int col = col0 + bj * 128;
;           f32x4 v[2];
; #pragma unroll
;           for (int n = 0; n < 2; ++n) v[n] = acc[ai][bj][m][n] * a + (*(const LAS f32x4*)(cl + bj * 128 + 4 * n)) * bb + *(const LAS f32x4*)(cl + 256 + bj * 128 + 4 * n);
;           if (SECT < 0) { u32x4 w; w[0] = pk2(v[0][0], v[0][1]); w[1] = pk2(v[0][2], v[0][3]); w[2] = pk2(v[1][0], v[1][1]); w[3] = pk2(v[1][2], v[1][3]); *(u32x4*)(h + (size_t)row * ld + col) = w; }
	v_pk_add_f32 v[178:179], v[144:145], v[178:179]
	v_pk_add_f32 v[144:145], v[142:143], v[172:173]
	v_cvt_pk_bf16_f32 v142, v158, v159
	v_mad_i64_i32 v[158:159], s[28:29], v168, s30, 0
	v_lshl_add_u64 v[158:159], v[158:159], 1, s[10:11]
	v_cvt_pk_bf16_f32 v143, v164, v165
	v_cvt_pk_bf16_f32 v144, v144, v145
	v_cvt_pk_bf16_f32 v145, v178, v179
	v_lshl_add_u64 v[158:159], v[158:159], 0, v[138:139]
	global_store_dwordx4 v[158:159], v[142:145], off
	ds_read_b128 v[142:145], v140 offset:512
	s_waitcnt lgkmcnt(0)
	v_pk_mul_f32 v[144:145], v[144:145], v[154:155] op_sel_hi:[1,0]
	v_pk_mul_f32 v[142:143], v[142:143], v[154:155] op_sel_hi:[1,0]
	v_pk_fma_f32 v[172:173], v[104:105], v[148:149], v[144:145] op_sel_hi:[1,0,1]
	v_pk_fma_f32 v[164:165], v[102:103], v[148:149], v[142:143] op_sel_hi:[1,0,1]
	ds_read_b128 v[142:145], v140 offset:1536
	s_waitcnt lgkmcnt(0)
	v_pk_add_f32 v[172:173], v[144:145], v[172:173]
	v_pk_add_f32 v[164:165], v[142:143], v[164:165]
	ds_read_b128 v[142:145], v140 offset:528
	s_waitcnt lgkmcnt(0)
	v_pk_mul_f32 v[144:145], v[144:145], v[154:155] op_sel_hi:[1,0]
	v_pk_mul_f32 v[142:143], v[142:143], v[154:155] op_sel_hi:[1,0]
	s_nop 0
	v_pk_fma_f32 v[154:155], v[98:99], v[148:149], v[142:143] op_sel_hi:[1,0,1]
	v_pk_fma_f32 v[148:149], v[100:101], v[148:149], v[144:145] op_sel_hi:[1,0,1]
	ds_read_b128 v[142:145], v140 offset:1552
	s_waitcnt lgkmcnt(0)
	v_pk_add_f32 v[148:149], v[144:145], v[148:149]
	v_pk_add_f32 v[144:145], v[142:143], v[154:155]
	v_cvt_pk_bf16_f32 v142, v164, v165
	v_cvt_pk_bf16_f32 v143, v172, v173
	v_cvt_pk_bf16_f32 v144, v144, v145
	v_cvt_pk_bf16_f32 v145, v148, v149
	global_store_dwordx4 v[158:159], v[142:145], off offset:256
	ds_read_b64 v[142:143], v141 offset:256
	s_waitcnt lgkmcnt(0)
	v_pk_mul_f32 v[142:143], v[142:143], s[44:45] op_sel_hi:[1,0]
	s_nop 0
	v_fma_f32 v143, -v142, v142, v143
	v_max_f32_e32 v143, 0, v143
	v_add_f32_e32 v143, 0x3727c5ac, v143
	v_cmp_gt_f32_e32 vcc, s27, v143
	v_mul_f32_e32 v144, 0x4b800000, v143
	s_nop 0
	v_cndmask_b32_e32 v143, v143, v144, vcc
	v_rsq_f32_e32 v143, v143
	s_nop 0
	v_mul_f32_e32 v144, 0x45800000, v143
	v_cndmask_b32_e32 v148, v143, v144, vcc
	v_mul_f32_e64 v154, v142, -v148
	ds_read_b128 v[142:145], v140
	ds_read_b128 v[202:205], v140 offset:16
	s_waitcnt lgkmcnt(0)
	v_pk_mul_f32 v[144:145], v[144:145], v[154:155] op_sel_hi:[1,0]
	v_pk_mul_f32 v[142:143], v[142:143], v[154:155] op_sel_hi:[1,0]
	v_pk_fma_f32 v[164:165], v[96:97], v[148:149], v[144:145] op_sel_hi:[1,0,1]
	v_pk_fma_f32 v[158:159], v[94:95], v[148:149], v[142:143] op_sel_hi:[1,0,1]
	ds_read_b128 v[142:145], v140 offset:1024
	s_waitcnt lgkmcnt(0)
	v_pk_add_f32 v[164:165], v[144:145], v[164:165]
	v_pk_add_f32 v[158:159], v[142:143], v[158:159]
	v_pk_mul_f32 v[142:143], v[204:205], v[154:155] op_sel_hi:[1,0]
	v_pk_mul_f32 v[144:145], v[202:203], v[154:155] op_sel_hi:[1,0]
	v_pk_fma_f32 v[178:179], v[92:93], v[148:149], v[142:143] op_sel_hi:[1,0,1]
	v_pk_fma_f32 v[172:173], v[90:91], v[148:149], v[144:145] op_sel_hi:[1,0,1]
	ds_read_b128 v[142:145], v140 offset:1040
	s_waitcnt lgkmcnt(0)
	v_pk_add_f32 v[178:179], v[144:145], v[178:179]
	v_pk_add_f32 v[144:145], v[142:143], v[172:173]
	v_cvt_pk_bf16_f32 v142, v158, v159
	v_mad_i64_i32 v[158:159], s[28:29], v166, s30, 0
	v_lshl_add_u64 v[158:159], v[158:159], 1, s[10:11]
	v_cvt_pk_bf16_f32 v143, v164, v165
	v_cvt_pk_bf16_f32 v144, v144, v145
	v_cvt_pk_bf16_f32 v145, v178, v179
	v_lshl_add_u64 v[158:159], v[158:159], 0, v[138:139]
	global_store_dwordx4 v[158:159], v[142:145], off
	ds_read_b128 v[142:145], v140 offset:512
	s_waitcnt lgkmcnt(0)
	v_pk_mul_f32 v[144:145], v[144:145], v[154:155] op_sel_hi:[1,0]
	v_pk_mul_f32 v[142:143], v[142:143], v[154:155] op_sel_hi:[1,0]
	v_pk_fma_f32 v[172:173], v[88:89], v[148:149], v[144:145] op_sel_hi:[1,0,1]
	v_pk_fma_f32 v[164:165], v[86:87], v[148:149], v[142:143] op_sel_hi:[1,0,1]
	ds_read_b128 v[142:145], v140 offset:1536
	s_waitcnt lgkmcnt(0)
	v_pk_add_f32 v[172:173], v[144:145], v[172:173]
	v_pk_add_f32 v[164:165], v[142:143], v[164:165]
	ds_read_b128 v[142:145], v140 offset:528
	s_waitcnt lgkmcnt(0)
	v_pk_mul_f32 v[144:145], v[144:145], v[154:155] op_sel_hi:[1,0]
	v_pk_mul_f32 v[142:143], v[142:143], v[154:155] op_sel_hi:[1,0]
	s_nop 0
	v_pk_fma_f32 v[154:155], v[82:83], v[148:149], v[142:143] op_sel_hi:[1,0,1]
	v_pk_fma_f32 v[148:149], v[84:85], v[148:149], v[144:145] op_sel_hi:[1,0,1]
	ds_read_b128 v[142:145], v140 offset:1552
	s_waitcnt lgkmcnt(0)
	v_pk_add_f32 v[148:149], v[144:145], v[148:149]
	v_pk_add_f32 v[144:145], v[142:143], v[154:155]
	v_cvt_pk_bf16_f32 v142, v164, v165
	v_cvt_pk_bf16_f32 v143, v172, v173
	v_cvt_pk_bf16_f32 v144, v144, v145
	v_cvt_pk_bf16_f32 v145, v148, v149
	global_store_dwordx4 v[158:159], v[142:145], off offset:256
	ds_read_b64 v[142:143], v141 offset:384
	s_waitcnt lgkmcnt(0)
	v_pk_mul_f32 v[142:143], v[142:143], s[44:45] op_sel_hi:[1,0]
	s_nop 0
	v_fma_f32 v143, -v142, v142, v143
	v_max_f32_e32 v143, 0, v143
	v_add_f32_e32 v143, 0x3727c5ac, v143
	v_cmp_gt_f32_e32 vcc, s27, v143
	v_mul_f32_e32 v144, 0x4b800000, v143
	s_nop 0
	v_cndmask_b32_e32 v143, v143, v144, vcc
	v_rsq_f32_e32 v143, v143
	s_nop 0
	v_mul_f32_e32 v144, 0x45800000, v143
	v_cndmask_b32_e32 v148, v143, v144, vcc
	v_mul_f32_e64 v154, v142, -v148
	ds_read_b128 v[142:145], v140
	ds_read_b128 v[202:205], v140 offset:16
	s_waitcnt lgkmcnt(0)
	v_pk_mul_f32 v[144:145], v[144:145], v[154:155] op_sel_hi:[1,0]
	v_pk_mul_f32 v[142:143], v[142:143], v[154:155] op_sel_hi:[1,0]
	v_pk_fma_f32 v[164:165], v[80:81], v[148:149], v[144:145] op_sel_hi:[1,0,1]
	v_pk_fma_f32 v[158:159], v[78:79], v[148:149], v[142:143] op_sel_hi:[1,0,1]
	ds_read_b128 v[142:145], v140 offset:1024
	s_waitcnt lgkmcnt(0)
; #define LAS __attribute__((address_space(3)))
; DI unsigned pk2(float a, float b) { typedef __bf16 bf2 __attribute__((ext_vector_type(2))); bf2 v; v[0] = (__bf16)a; v[1] = (__bf16)b; return __builtin_bit_cast(unsigned, v); }
;   template <int SECT>
;   DI void body(const f32x4 (&acc)[2][2][4][2], const pg8::Unit& u, int wr, int wc, int fr, int fq, LAS unsigned char* lds, int ui, int wid) const {
;     ...
;       for (int m = 0; m < 4; ++m) {
;         const int row = u.pm * 256 + ai * 128 + wr * 64 + m * 16 + fr; float a, bb;
;         { typedef float f32x2_ __attribute__((ext_vector_type(2))); const f32x2_ sv = *(const LAS f32x2_*)(sl + ai * 128 + (m * 16 + fr_) * 2);
;           const float mu = sv.x * (1.0f / 1024.0f), var = fmaxf(sv.y * (1.0f / 1024.0f) - mu * mu, 0.f), rstd = rsqrtf(var + 1e-5f); a = rstd; bb = -rstd * mu; }
; #pragma unroll
;         for (int bj = 0; bj < 2; ++bj) {
;           const int col = col0 + bj * 128;
;           f32x4 v[2];
; #pragma unroll
;           for (int n = 0; n < 2; ++n) v[n] = acc[ai][bj][m][n] * a + (*(const LAS f32x4*)(cl + bj * 128 + 4 * n)) * bb + *(const LAS f32x4*)(cl + 256 + bj * 128 + 4 * n);
;           if (SECT < 0) { u32x4 w; w[0] = pk2(v[0][0], v[0][1]); w[1] = pk2(v[0][2], v[0][3]); w[2] = pk2(v[1][0], v[1][1]); w[3] = pk2(v[1][2], v[1][3]); *(u32x4*)(h + (size_t)row * ld + col) = w; }
	v_pk_add_f32 v[164:165], v[144:145], v[164:165]
	v_pk_add_f32 v[158:159], v[142:143], v[158:159]
	v_pk_mul_f32 v[142:143], v[204:205], v[154:155] op_sel_hi:[1,0]
	v_pk_mul_f32 v[144:145], v[202:203], v[154:155] op_sel_hi:[1,0]
	v_pk_fma_f32 v[178:179], v[76:77], v[148:149], v[142:143] op_sel_hi:[1,0,1]
	v_pk_fma_f32 v[172:173], v[74:75], v[148:149], v[144:145] op_sel_hi:[1,0,1]
	ds_read_b128 v[142:145], v140 offset:1040
	s_waitcnt lgkmcnt(0)
	v_pk_add_f32 v[178:179], v[144:145], v[178:179]
	v_pk_add_f32 v[144:145], v[142:143], v[172:173]
	v_cvt_pk_bf16_f32 v142, v158, v159
	v_mad_i64_i32 v[158:159], s[28:29], v162, s30, 0
	v_lshl_add_u64 v[158:159], v[158:159], 1, s[10:11]
	v_cvt_pk_bf16_f32 v143, v164, v165
	v_cvt_pk_bf16_f32 v144, v144, v145
	v_cvt_pk_bf16_f32 v145, v178, v179
	v_lshl_add_u64 v[158:159], v[158:159], 0, v[138:139]
	global_store_dwordx4 v[158:159], v[142:145], off
	ds_read_b128 v[142:145], v140 offset:512
	s_waitcnt lgkmcnt(0)
	v_pk_mul_f32 v[144:145], v[144:145], v[154:155] op_sel_hi:[1,0]
	v_pk_mul_f32 v[142:143], v[142:143], v[154:155] op_sel_hi:[1,0]
	v_pk_fma_f32 v[172:173], v[72:73], v[148:149], v[144:145] op_sel_hi:[1,0,1]
	v_pk_fma_f32 v[164:165], v[70:71], v[148:149], v[142:143] op_sel_hi:[1,0,1]
	ds_read_b128 v[142:145], v140 offset:1536
	s_waitcnt lgkmcnt(0)
	v_pk_add_f32 v[172:173], v[144:145], v[172:173]
	v_pk_add_f32 v[164:165], v[142:143], v[164:165]
	ds_read_b128 v[142:145], v140 offset:528
	s_waitcnt lgkmcnt(0)
	v_pk_mul_f32 v[144:145], v[144:145], v[154:155] op_sel_hi:[1,0]
	v_pk_mul_f32 v[142:143], v[142:143], v[154:155] op_sel_hi:[1,0]
	s_nop 0
	v_pk_fma_f32 v[154:155], v[66:67], v[148:149], v[142:143] op_sel_hi:[1,0,1]
	v_pk_fma_f32 v[148:149], v[68:69], v[148:149], v[144:145] op_sel_hi:[1,0,1]
	ds_read_b128 v[142:145], v140 offset:1552
	s_waitcnt lgkmcnt(0)
	v_pk_add_f32 v[148:149], v[144:145], v[148:149]
	v_pk_add_f32 v[144:145], v[142:143], v[154:155]
	v_cvt_pk_bf16_f32 v142, v164, v165
	v_cvt_pk_bf16_f32 v143, v172, v173
	v_cvt_pk_bf16_f32 v144, v144, v145
	v_cvt_pk_bf16_f32 v145, v148, v149
	global_store_dwordx4 v[158:159], v[142:145], off offset:256
	ds_read_b64 v[142:143], v141 offset:512
	s_waitcnt lgkmcnt(0)
	v_pk_mul_f32 v[142:143], v[142:143], s[44:45] op_sel_hi:[1,0]
	s_nop 0
	v_fma_f32 v143, -v142, v142, v143
	v_max_f32_e32 v143, 0, v143
	v_add_f32_e32 v143, 0x3727c5ac, v143
	v_cmp_gt_f32_e32 vcc, s27, v143
	v_mul_f32_e32 v144, 0x4b800000, v143
	s_nop 0
	v_cndmask_b32_e32 v143, v143, v144, vcc
	v_rsq_f32_e32 v143, v143
	s_nop 0
	v_mul_f32_e32 v144, 0x45800000, v143
	v_cndmask_b32_e32 v148, v143, v144, vcc
	v_mul_f32_e64 v154, v142, -v148
	ds_read_b128 v[142:145], v140
	ds_read_b128 v[202:205], v140 offset:16
	s_waitcnt lgkmcnt(0)
	v_pk_mul_f32 v[144:145], v[144:145], v[154:155] op_sel_hi:[1,0]
	v_pk_mul_f32 v[142:143], v[142:143], v[154:155] op_sel_hi:[1,0]
	v_pk_fma_f32 v[164:165], v[64:65], v[148:149], v[144:145] op_sel_hi:[1,0,1]
	v_pk_fma_f32 v[158:159], v[62:63], v[148:149], v[142:143] op_sel_hi:[1,0,1]
	ds_read_b128 v[142:145], v140 offset:1024
	s_waitcnt lgkmcnt(0)
	v_pk_add_f32 v[164:165], v[144:145], v[164:165]
	v_pk_add_f32 v[158:159], v[142:143], v[158:159]
	v_pk_mul_f32 v[142:143], v[204:205], v[154:155] op_sel_hi:[1,0]
	v_pk_mul_f32 v[144:145], v[202:203], v[154:155] op_sel_hi:[1,0]
	v_pk_fma_f32 v[178:179], v[60:61], v[148:149], v[142:143] op_sel_hi:[1,0,1]
	v_pk_fma_f32 v[172:173], v[58:59], v[148:149], v[144:145] op_sel_hi:[1,0,1]
	ds_read_b128 v[142:145], v140 offset:1040
	s_waitcnt lgkmcnt(0)
	v_pk_add_f32 v[178:179], v[144:145], v[178:179]
	v_pk_add_f32 v[144:145], v[142:143], v[172:173]
	v_cvt_pk_bf16_f32 v142, v158, v159
	v_mad_i64_i32 v[158:159], s[28:29], v160, s30, 0
	v_lshl_add_u64 v[158:159], v[158:159], 1, s[10:11]
	v_cvt_pk_bf16_f32 v143, v164, v165
	v_cvt_pk_bf16_f32 v144, v144, v145
	v_cvt_pk_bf16_f32 v145, v178, v179
	v_lshl_add_u64 v[158:159], v[158:159], 0, v[138:139]
	global_store_dwordx4 v[158:159], v[142:145], off
	ds_read_b128 v[142:145], v140 offset:512
	s_waitcnt lgkmcnt(0)
	v_pk_mul_f32 v[144:145], v[144:145], v[154:155] op_sel_hi:[1,0]
	v_pk_mul_f32 v[142:143], v[142:143], v[154:155] op_sel_hi:[1,0]
	v_pk_fma_f32 v[172:173], v[56:57], v[148:149], v[144:145] op_sel_hi:[1,0,1]
	v_pk_fma_f32 v[164:165], v[54:55], v[148:149], v[142:143] op_sel_hi:[1,0,1]
	ds_read_b128 v[142:145], v140 offset:1536
	s_waitcnt lgkmcnt(0)
	v_pk_add_f32 v[172:173], v[144:145], v[172:173]
	v_pk_add_f32 v[164:165], v[142:143], v[164:165]
	ds_read_b128 v[142:145], v140 offset:528
	s_waitcnt lgkmcnt(0)
	v_pk_mul_f32 v[144:145], v[144:145], v[154:155] op_sel_hi:[1,0]
	v_pk_mul_f32 v[142:143], v[142:143], v[154:155] op_sel_hi:[1,0]
	s_nop 0
	v_pk_fma_f32 v[154:155], v[50:51], v[148:149], v[142:143] op_sel_hi:[1,0,1]
	v_pk_fma_f32 v[148:149], v[52:53], v[148:149], v[144:145] op_sel_hi:[1,0,1]
	ds_read_b128 v[142:145], v140 offset:1552
	s_waitcnt lgkmcnt(0)
	v_pk_add_f32 v[148:149], v[144:145], v[148:149]
	v_pk_add_f32 v[144:145], v[142:143], v[154:155]
	v_cvt_pk_bf16_f32 v142, v164, v165
	v_cvt_pk_bf16_f32 v143, v172, v173
	v_cvt_pk_bf16_f32 v144, v144, v145
	v_cvt_pk_bf16_f32 v145, v148, v149
	global_store_dwordx4 v[158:159], v[142:145], off offset:256
	ds_read_b64 v[142:143], v141 offset:640
	s_waitcnt lgkmcnt(0)
	v_pk_mul_f32 v[142:143], v[142:143], s[44:45] op_sel_hi:[1,0]
	s_nop 0
	v_fma_f32 v143, -v142, v142, v143
	v_max_f32_e32 v143, 0, v143
	v_add_f32_e32 v143, 0x3727c5ac, v143
	v_cmp_gt_f32_e32 vcc, s27, v143
	v_mul_f32_e32 v144, 0x4b800000, v143
	s_nop 0
	v_cndmask_b32_e32 v143, v143, v144, vcc
	v_rsq_f32_e32 v143, v143
	s_nop 0
	v_mul_f32_e32 v144, 0x45800000, v143
	v_cndmask_b32_e32 v148, v143, v144, vcc
	v_mul_f32_e64 v154, v142, -v148
	ds_read_b128 v[142:145], v140
	ds_read_b128 v[202:205], v140 offset:16
	s_waitcnt lgkmcnt(0)
; #define LAS __attribute__((address_space(3)))
; DI unsigned pk2(float a, float b) { typedef __bf16 bf2 __attribute__((ext_vector_type(2))); bf2 v; v[0] = (__bf16)a; v[1] = (__bf16)b; return __builtin_bit_cast(unsigned, v); }
;   template <int SECT>
;   DI void body(const f32x4 (&acc)[2][2][4][2], const pg8::Unit& u, int wr, int wc, int fr, int fq, LAS unsigned char* lds, int ui, int wid) const {
;     ...
;       for (int m = 0; m < 4; ++m) {
;         const int row = u.pm * 256 + ai * 128 + wr * 64 + m * 16 + fr; float a, bb;
;         { typedef float f32x2_ __attribute__((ext_vector_type(2))); const f32x2_ sv = *(const LAS f32x2_*)(sl + ai * 128 + (m * 16 + fr_) * 2);
;           const float mu = sv.x * (1.0f / 1024.0f), var = fmaxf(sv.y * (1.0f / 1024.0f) - mu * mu, 0.f), rstd = rsqrtf(var + 1e-5f); a = rstd; bb = -rstd * mu; }
; #pragma unroll
;         for (int bj = 0; bj < 2; ++bj) {
;           const int col = col0 + bj * 128;
;           f32x4 v[2];
; #pragma unroll
;           for (int n = 0; n < 2; ++n) v[n] = acc[ai][bj][m][n] * a + (*(const LAS f32x4*)(cl + bj * 128 + 4 * n)) * bb + *(const LAS f32x4*)(cl + 256 + bj * 128 + 4 * n);
;           if (SECT < 0) { u32x4 w; w[0] = pk2(v[0][0], v[0][1]); w[1] = pk2(v[0][2], v[0][3]); w[2] = pk2(v[1][0], v[1][1]); w[3] = pk2(v[1][2], v[1][3]); *(u32x4*)(h + (size_t)row * ld + col) = w; }
	v_pk_mul_f32 v[144:145], v[144:145], v[154:155] op_sel_hi:[1,0]
	v_pk_mul_f32 v[142:143], v[142:143], v[154:155] op_sel_hi:[1,0]
	v_pk_fma_f32 v[164:165], v[48:49], v[148:149], v[144:145] op_sel_hi:[1,0,1]
	v_pk_fma_f32 v[158:159], v[46:47], v[148:149], v[142:143] op_sel_hi:[1,0,1]
	ds_read_b128 v[142:145], v140 offset:1024
	s_waitcnt lgkmcnt(0)
	v_pk_add_f32 v[164:165], v[144:145], v[164:165]
	v_pk_add_f32 v[158:159], v[142:143], v[158:159]
	v_pk_mul_f32 v[142:143], v[204:205], v[154:155] op_sel_hi:[1,0]
	v_pk_mul_f32 v[144:145], v[202:203], v[154:155] op_sel_hi:[1,0]
	v_pk_fma_f32 v[178:179], v[44:45], v[148:149], v[142:143] op_sel_hi:[1,0,1]
	v_pk_fma_f32 v[172:173], v[42:43], v[148:149], v[144:145] op_sel_hi:[1,0,1]
	ds_read_b128 v[142:145], v140 offset:1040
	s_waitcnt lgkmcnt(0)
	v_pk_add_f32 v[178:179], v[144:145], v[178:179]
	v_pk_add_f32 v[144:145], v[142:143], v[172:173]
	v_cvt_pk_bf16_f32 v142, v158, v159
	v_mad_i64_i32 v[158:159], s[28:29], v156, s30, 0
	v_lshl_add_u64 v[158:159], v[158:159], 1, s[10:11]
	v_cvt_pk_bf16_f32 v143, v164, v165
	v_cvt_pk_bf16_f32 v144, v144, v145
	v_cvt_pk_bf16_f32 v145, v178, v179
	v_lshl_add_u64 v[158:159], v[158:159], 0, v[138:139]
	global_store_dwordx4 v[158:159], v[142:145], off
	ds_read_b128 v[142:145], v140 offset:512
	s_waitcnt lgkmcnt(0)
	v_pk_mul_f32 v[144:145], v[144:145], v[154:155] op_sel_hi:[1,0]
	v_pk_mul_f32 v[142:143], v[142:143], v[154:155] op_sel_hi:[1,0]
	v_pk_fma_f32 v[172:173], v[40:41], v[148:149], v[144:145] op_sel_hi:[1,0,1]
	v_pk_fma_f32 v[164:165], v[38:39], v[148:149], v[142:143] op_sel_hi:[1,0,1]
	ds_read_b128 v[142:145], v140 offset:1536
	s_waitcnt lgkmcnt(0)
	v_pk_add_f32 v[172:173], v[144:145], v[172:173]
	v_pk_add_f32 v[164:165], v[142:143], v[164:165]
	ds_read_b128 v[142:145], v140 offset:528
	s_waitcnt lgkmcnt(0)
	v_pk_mul_f32 v[144:145], v[144:145], v[154:155] op_sel_hi:[1,0]
	v_pk_mul_f32 v[142:143], v[142:143], v[154:155] op_sel_hi:[1,0]
	s_nop 0
	v_pk_fma_f32 v[154:155], v[34:35], v[148:149], v[142:143] op_sel_hi:[1,0,1]
	v_pk_fma_f32 v[148:149], v[36:37], v[148:149], v[144:145] op_sel_hi:[1,0,1]
	ds_read_b128 v[142:145], v140 offset:1552
	s_waitcnt lgkmcnt(0)
	v_pk_add_f32 v[148:149], v[144:145], v[148:149]
	v_pk_add_f32 v[144:145], v[142:143], v[154:155]
	v_cvt_pk_bf16_f32 v142, v164, v165
	v_cvt_pk_bf16_f32 v143, v172, v173
	v_cvt_pk_bf16_f32 v144, v144, v145
	v_cvt_pk_bf16_f32 v145, v148, v149
	global_store_dwordx4 v[158:159], v[142:145], off offset:256
	ds_read_b64 v[142:143], v141 offset:768
	s_waitcnt lgkmcnt(0)
	v_pk_mul_f32 v[142:143], v[142:143], s[44:45] op_sel_hi:[1,0]
	s_nop 0
	v_fma_f32 v143, -v142, v142, v143
	v_max_f32_e32 v143, 0, v143
	v_add_f32_e32 v143, 0x3727c5ac, v143
	v_cmp_gt_f32_e32 vcc, s27, v143
	v_mul_f32_e32 v144, 0x4b800000, v143
	s_nop 0
	v_cndmask_b32_e32 v143, v143, v144, vcc
	v_rsq_f32_e32 v143, v143
	s_nop 0
	v_mul_f32_e32 v144, 0x45800000, v143
	v_cndmask_b32_e32 v148, v143, v144, vcc
	v_mul_f32_e64 v154, v142, -v148
	ds_read_b128 v[142:145], v140
	ds_read_b128 v[202:205], v140 offset:16
	s_waitcnt lgkmcnt(0)
	v_pk_mul_f32 v[144:145], v[144:145], v[154:155] op_sel_hi:[1,0]
	v_pk_mul_f32 v[142:143], v[142:143], v[154:155] op_sel_hi:[1,0]
	v_pk_fma_f32 v[164:165], v[30:31], v[148:149], v[144:145] op_sel_hi:[1,0,1]
	v_pk_fma_f32 v[158:159], v[28:29], v[148:149], v[142:143] op_sel_hi:[1,0,1]
	ds_read_b128 v[142:145], v140 offset:1024
	s_waitcnt lgkmcnt(0)
	v_pk_add_f32 v[164:165], v[144:145], v[164:165]
	v_pk_add_f32 v[158:159], v[142:143], v[158:159]
	v_pk_mul_f32 v[142:143], v[204:205], v[154:155] op_sel_hi:[1,0]
	v_pk_mul_f32 v[144:145], v[202:203], v[154:155] op_sel_hi:[1,0]
	v_pk_fma_f32 v[178:179], v[26:27], v[148:149], v[142:143] op_sel_hi:[1,0,1]
	v_pk_fma_f32 v[172:173], v[24:25], v[148:149], v[144:145] op_sel_hi:[1,0,1]
	ds_read_b128 v[142:145], v140 offset:1040
	s_waitcnt lgkmcnt(0)
	v_pk_add_f32 v[178:179], v[144:145], v[178:179]
	v_pk_add_f32 v[144:145], v[142:143], v[172:173]
	v_cvt_pk_bf16_f32 v142, v158, v159
	v_mad_i64_i32 v[158:159], s[28:29], v152, s30, 0
	v_lshl_add_u64 v[158:159], v[158:159], 1, s[10:11]
	v_cvt_pk_bf16_f32 v143, v164, v165
	v_cvt_pk_bf16_f32 v144, v144, v145
	v_cvt_pk_bf16_f32 v145, v178, v179
	v_lshl_add_u64 v[158:159], v[158:159], 0, v[138:139]
	global_store_dwordx4 v[158:159], v[142:145], off
	ds_read_b128 v[142:145], v140 offset:512
	s_waitcnt lgkmcnt(0)
; #define LAS __attribute__((address_space(3)))
; DI unsigned pk2(float a, float b) { typedef __bf16 bf2 __attribute__((ext_vector_type(2))); bf2 v; v[0] = (__bf16)a; v[1] = (__bf16)b; return __builtin_bit_cast(unsigned, v); }
;   template <int SECT>
;   DI void body(const f32x4 (&acc)[2][2][4][2], const pg8::Unit& u, int wr, int wc, int fr, int fq, LAS unsigned char* lds, int ui, int wid) const {
;     ...
;       for (int m = 0; m < 4; ++m) {
;         const int row = u.pm * 256 + ai * 128 + wr * 64 + m * 16 + fr; float a, bb;
;         { typedef float f32x2_ __attribute__((ext_vector_type(2))); const f32x2_ sv = *(const LAS f32x2_*)(sl + ai * 128 + (m * 16 + fr_) * 2);
;           const float mu = sv.x * (1.0f / 1024.0f), var = fmaxf(sv.y * (1.0f / 1024.0f) - mu * mu, 0.f), rstd = rsqrtf(var + 1e-5f); a = rstd; bb = -rstd * mu; }
; #pragma unroll
;         for (int bj = 0; bj < 2; ++bj) {
;           const int col = col0 + bj * 128;
;           f32x4 v[2];
; #pragma unroll
;           for (int n = 0; n < 2; ++n) v[n] = acc[ai][bj][m][n] * a + (*(const LAS f32x4*)(cl + bj * 128 + 4 * n)) * bb + *(const LAS f32x4*)(cl + 256 + bj * 128 + 4 * n);
;           if (SECT < 0) { u32x4 w; w[0] = pk2(v[0][0], v[0][1]); w[1] = pk2(v[0][2], v[0][3]); w[2] = pk2(v[1][0], v[1][1]); w[3] = pk2(v[1][2], v[1][3]); *(u32x4*)(h + (size_t)row * ld + col) = w; }
	v_pk_mul_f32 v[144:145], v[144:145], v[154:155] op_sel_hi:[1,0]
	v_pk_mul_f32 v[142:143], v[142:143], v[154:155] op_sel_hi:[1,0]
	v_pk_fma_f32 v[172:173], v[22:23], v[148:149], v[144:145] op_sel_hi:[1,0,1]
	v_pk_fma_f32 v[164:165], v[20:21], v[148:149], v[142:143] op_sel_hi:[1,0,1]
	ds_read_b128 v[142:145], v140 offset:1536
	s_waitcnt lgkmcnt(0)
	v_pk_add_f32 v[172:173], v[144:145], v[172:173]
	v_pk_add_f32 v[164:165], v[142:143], v[164:165]
	ds_read_b128 v[142:145], v140 offset:528
	s_waitcnt lgkmcnt(0)
	v_pk_mul_f32 v[144:145], v[144:145], v[154:155] op_sel_hi:[1,0]
	v_pk_mul_f32 v[142:143], v[142:143], v[154:155] op_sel_hi:[1,0]
	s_nop 0
	v_pk_fma_f32 v[154:155], v[16:17], v[148:149], v[142:143] op_sel_hi:[1,0,1]
	v_pk_fma_f32 v[148:149], v[18:19], v[148:149], v[144:145] op_sel_hi:[1,0,1]
	ds_read_b128 v[142:145], v140 offset:1552
	s_waitcnt lgkmcnt(0)
	v_pk_add_f32 v[148:149], v[144:145], v[148:149]
	v_pk_add_f32 v[144:145], v[142:143], v[154:155]
	v_cvt_pk_bf16_f32 v142, v164, v165
	v_cvt_pk_bf16_f32 v143, v172, v173
	v_cvt_pk_bf16_f32 v144, v144, v145
	v_cvt_pk_bf16_f32 v145, v148, v149
	global_store_dwordx4 v[158:159], v[142:145], off offset:256
	ds_read_b64 v[142:143], v141 offset:896
	s_waitcnt lgkmcnt(0)
	v_pk_mul_f32 v[142:143], v[142:143], s[44:45] op_sel_hi:[1,0]
	s_nop 0
	v_fma_f32 v141, -v142, v142, v143
	v_max_f32_e32 v141, 0, v141
	v_add_f32_e32 v141, 0x3727c5ac, v141
	v_cmp_gt_f32_e32 vcc, s27, v141
	v_mul_f32_e32 v143, 0x4b800000, v141
	s_nop 0
	v_cndmask_b32_e32 v141, v141, v143, vcc
	v_rsq_f32_e32 v141, v141
	s_nop 0
	v_mul_f32_e32 v143, 0x45800000, v141
	v_cndmask_b32_e32 v148, v141, v143, vcc
	v_mul_f32_e64 v154, v142, -v148
	ds_read_b128 v[142:145], v140
	ds_read_b128 v[202:205], v140 offset:16
	s_waitcnt lgkmcnt(0)
	v_pk_mul_f32 v[144:145], v[144:145], v[154:155] op_sel_hi:[1,0]
	v_pk_mul_f32 v[142:143], v[142:143], v[154:155] op_sel_hi:[1,0]
	v_pk_fma_f32 v[164:165], v[14:15], v[148:149], v[144:145] op_sel_hi:[1,0,1]
	v_pk_fma_f32 v[158:159], v[12:13], v[148:149], v[142:143] op_sel_hi:[1,0,1]
	ds_read_b128 v[142:145], v140 offset:1024
	s_waitcnt lgkmcnt(0)
	v_pk_add_f32 v[164:165], v[144:145], v[164:165]
	v_pk_add_f32 v[158:159], v[142:143], v[158:159]
	v_pk_mul_f32 v[142:143], v[204:205], v[154:155] op_sel_hi:[1,0]
	v_pk_mul_f32 v[144:145], v[202:203], v[154:155] op_sel_hi:[1,0]
	v_pk_fma_f32 v[178:179], v[10:11], v[148:149], v[142:143] op_sel_hi:[1,0,1]
	v_pk_fma_f32 v[172:173], v[8:9], v[148:149], v[144:145] op_sel_hi:[1,0,1]
	ds_read_b128 v[142:145], v140 offset:1040
	s_waitcnt lgkmcnt(0)
	v_pk_add_f32 v[178:179], v[144:145], v[178:179]
	v_pk_add_f32 v[144:145], v[142:143], v[172:173]
	v_cvt_pk_bf16_f32 v142, v158, v159
	v_mad_i64_i32 v[158:159], s[28:29], v150, s30, 0
	v_lshl_add_u64 v[158:159], v[158:159], 1, s[10:11]
	v_cvt_pk_bf16_f32 v143, v164, v165
	v_cvt_pk_bf16_f32 v144, v144, v145
	v_cvt_pk_bf16_f32 v145, v178, v179
	v_lshl_add_u64 v[158:159], v[158:159], 0, v[138:139]
	global_store_dwordx4 v[158:159], v[142:145], off
	ds_read_b128 v[142:145], v140 offset:512
	s_mov_b64 s[28:29], 0
	s_waitcnt lgkmcnt(0)
	v_pk_mul_f32 v[142:143], v[142:143], v[154:155] op_sel_hi:[1,0]
	v_pk_mul_f32 v[138:139], v[144:145], v[154:155] op_sel_hi:[1,0]
	v_pk_fma_f32 v[164:165], v[4:5], v[148:149], v[142:143] op_sel_hi:[1,0,1]
	ds_read_b128 v[142:145], v140 offset:1536
	v_pk_fma_f32 v[138:139], v[6:7], v[148:149], v[138:139] op_sel_hi:[1,0,1]
	s_waitcnt lgkmcnt(0)
	v_pk_add_f32 v[164:165], v[142:143], v[164:165]
	v_pk_add_f32 v[172:173], v[144:145], v[138:139]
	ds_read_b128 v[142:145], v140 offset:528
	s_waitcnt lgkmcnt(0)
	v_pk_mul_f32 v[138:139], v[144:145], v[154:155] op_sel_hi:[1,0]
	s_nop 0
	v_pk_fma_f32 v[144:145], v[2:3], v[148:149], v[138:139] op_sel_hi:[1,0,1]
	ds_read_b128 v[138:141], v140 offset:1552
	v_pk_mul_f32 v[142:143], v[142:143], v[154:155] op_sel_hi:[1,0]
	s_waitcnt lgkmcnt(0)
	v_pk_add_f32 v[144:145], v[140:141], v[144:145]
	v_pk_fma_f32 v[142:143], v[0:1], v[148:149], v[142:143] op_sel_hi:[1,0,1]
	s_nop 0
	v_pk_add_f32 v[140:141], v[138:139], v[142:143]
	v_cvt_pk_bf16_f32 v138, v164, v165
	v_cvt_pk_bf16_f32 v139, v172, v173
	v_cvt_pk_bf16_f32 v140, v140, v141
	v_cvt_pk_bf16_f32 v141, v144, v145
	global_store_dwordx4 v[158:159], v[138:141], off offset:256

; #define PG8_STAGE(bufoff, gbase, voff) do { _Pragma("unroll") for (int _i = 0; _i < 2; ++_i) \
;     __builtin_amdgcn_global_load_lds((const unsigned*)((const char*)(gbase) + (voff)[_i]), (LAS unsigned*)(lds + (bufoff) + ldsw + _i * 8192), 16, 0, 0); } while (0)
; #define PG8_LDA(dst, b, h) do { _Pragma("unroll") for (int m = 0; m < 4; ++m) _Pragma("unroll") for (int k = 0; k < 2; ++k) dst[m][k] = *(const LAS bf16x8*)(lds + PG8_SA(b, h) + aoff + m * 2048 + k * 1024); } while (0)
; #define PG8_LDB(dst, b, h) do { _Pragma("unroll") for (int n = 0; n < 2; ++n) _Pragma("unroll") for (int k = 0; k < 2; ++k) dst[n][k] = *(const LAS bf16x8*)(lds + PG8_SB(b, h) + boff + n * 2048 + k * 1024); } while (0)
; #define PG8_WAIT_L(n) asm volatile("s_waitcnt lgkmcnt(" #n ")" ::: "memory")
; #define PG8_BAR __builtin_amdgcn_s_barrier()
; #define PG8_SCHED __builtin_amdgcn_sched_barrier(0)
; template <class Epi>
; DI void gemm_phase(int wv, LAS unsigned char* lds, const Gemm g, const StaticOrder& S, const Epi& E) {
;     ...
;     const bool has_next = S.next(ui + 1, nxt);
;     const char* nA = has_next ? (const char*)g.A + (size_t)nxt.pm * tstep : cA; const char* nB = has_next ? (const char*)g.Bt + (size_t)nxt.pn * tstep : cB;
;     for (int t = 0; t < nt; t += 2) {
;       const bool last = (t == nt - 2);
;       const char* a1 = cA + (size_t)(t + 1) * kstep;
;       const char* a2 = last ? nA : cA + (size_t)(t + 2) * kstep; const char* b2 = last ? nB : cB + (size_t)(t + 2) * kstep;
;       const char* a3 = a2 + kstep; const char* b3 = b2 + kstep;
;       PG8_LDB(B0, 0, 0); PG8_SCHED; PG8_LDA(At, 0, 0); PG8_STAGE(PG8_SA(1, 1), a1 + hstep, voffA);
;       PG8_WAIT_L(8); PG8_BAR; PG8_WAIT_L(0); PG8_MMA(0, 0, At, B0); PG8_BAR; PG8_SCHED;
;       PG8_LDB(B1, 0, 1); PG8_STAGE(PG8_SB(0, 0), b2, voffA);
;       PG8_BAR; PG8_WAIT_L(0); PG8_MMA(0, 1, At, B1); PG8_BAR;
;     ...
; #pragma unroll
;     for (int a = 0; a < 2; ++a)
; #pragma unroll
;       for (int b = 0; b < 2; ++b)
; #pragma unroll
;         for (int m = 0; m < 4; ++m)
; #pragma unroll
;           for (int n = 0; n < 2; ++n) acc[a][b][m][n] = (f32x4){0.f, 0.f, 0.f, 0.f};
;     cur = nxt; cA = nA; cB = nB; ++ui;
.LBB0_889:
	s_add_u32 s30, s30, 0x80
	s_addc_u32 s31, s31, 0
	s_add_u32 s95, s34, 0x100
	v_mov_b32_e32 v0, 0
	s_addc_u32 vcc_lo, s35, 0
	s_mov_b32 s34, 0
	s_waitcnt lgkmcnt(0)
	v_mov_b32_e32 v1, v0
	v_mov_b64_e32 v[2:3], v[0:1]
	v_mov_b64_e32 v[4:5], v[0:1]
	v_mov_b64_e32 v[6:7], v[0:1]
	v_mov_b64_e32 v[16:17], v[0:1]
	v_mov_b64_e32 v[18:19], v[0:1]
	v_mov_b64_e32 v[20:21], v[0:1]
	v_mov_b64_e32 v[22:23], v[0:1]
	v_mov_b64_e32 v[34:35], v[0:1]
	v_mov_b64_e32 v[36:37], v[0:1]
	v_mov_b64_e32 v[38:39], v[0:1]
	v_mov_b64_e32 v[40:41], v[0:1]
	v_mov_b64_e32 v[50:51], v[0:1]
	v_mov_b64_e32 v[52:53], v[0:1]
	v_mov_b64_e32 v[54:55], v[0:1]
	v_mov_b64_e32 v[56:57], v[0:1]
	v_mov_b64_e32 v[8:9], v[0:1]
	v_mov_b64_e32 v[10:11], v[0:1]
	v_mov_b64_e32 v[12:13], v[0:1]
	v_mov_b64_e32 v[14:15], v[0:1]
	v_mov_b64_e32 v[24:25], v[0:1]
	v_mov_b64_e32 v[26:27], v[0:1]
	v_mov_b64_e32 v[28:29], v[0:1]
	v_mov_b64_e32 v[30:31], v[0:1]
	v_mov_b64_e32 v[42:43], v[0:1]
	v_mov_b64_e32 v[44:45], v[0:1]
	v_mov_b64_e32 v[46:47], v[0:1]
	v_mov_b64_e32 v[48:49], v[0:1]
	v_mov_b64_e32 v[62:63], v[0:1]
	v_mov_b64_e32 v[64:65], v[0:1]
	v_mov_b64_e32 v[70:71], v[0:1]
	v_mov_b64_e32 v[72:73], v[0:1]
	v_mov_b64_e32 v[74:75], v[0:1]
	v_mov_b64_e32 v[76:77], v[0:1]
	v_mov_b64_e32 v[78:79], v[0:1]
	v_mov_b64_e32 v[80:81], v[0:1]
	v_mov_b64_e32 v[90:91], v[0:1]
	v_mov_b64_e32 v[92:93], v[0:1]
	v_mov_b64_e32 v[94:95], v[0:1]
	v_mov_b64_e32 v[96:97], v[0:1]
	v_mov_b64_e32 v[106:107], v[0:1]
	v_mov_b64_e32 v[108:109], v[0:1]
	v_mov_b64_e32 v[110:111], v[0:1]
	v_mov_b64_e32 v[112:113], v[0:1]
	s_waitcnt vmcnt(0)
	v_mov_b64_e32 v[122:123], v[0:1]
	v_mov_b64_e32 v[124:125], v[0:1]
	v_mov_b64_e32 v[126:127], v[0:1]
	v_mov_b64_e32 v[128:129], v[0:1]
	v_mov_b64_e32 v[82:83], v[0:1]
	v_mov_b64_e32 v[84:85], v[0:1]
	v_mov_b64_e32 v[86:87], v[0:1]
	v_mov_b64_e32 v[88:89], v[0:1]
	v_mov_b64_e32 v[98:99], v[0:1]
	v_mov_b64_e32 v[100:101], v[0:1]
	v_mov_b64_e32 v[102:103], v[0:1]
	v_mov_b64_e32 v[104:105], v[0:1]
	v_mov_b64_e32 v[114:115], v[0:1]
	v_mov_b64_e32 v[116:117], v[0:1]
	v_mov_b64_e32 v[118:119], v[0:1]
	v_mov_b64_e32 v[120:121], v[0:1]
	v_mov_b64_e32 v[134:135], v[0:1]
	v_mov_b64_e32 v[136:137], v[0:1]
	v_mov_b64_e32 v[162:163], v[0:1]
	v_mov_b64_e32 v[164:165], v[0:1]
	s_cmpk_lt_u32 s69, 0x100
	s_cbranch_scc1 .Lgprio_c
	s_setprio 1
.Lgprio_c:
.LBB0_890:
	s_add_i32 vcc_hi, s34, 2
	s_add_u32 s36, s30, 0x80
	s_addc_u32 s35, s31, 0
	s_add_i32 s41, 0, 0x10000
	v_add_u32_e32 v138, s41, v246
	ds_read_b128 v[58:61], v138
	ds_read_b128 v[66:69], v138 offset:1024
	ds_read_b128 v[130:133], v138 offset:2048
	ds_read_b128 v[138:141], v138 offset:3072
	s_cmp_eq_u32 s60, s34
	s_cselect_b32 s34, s0, s36
	s_cselect_b32 s35, s1, s35
	s_cselect_b32 s37, s29, vcc_lo
	s_cselect_b32 s36, s28, s95
	v_lshl_add_u64 v[178:179], s[30:31], 0, v[206:207]
	s_add_i32 m0, s62, 0xc000
	ds_read_b128 v[142:145], v248
	ds_read_b128 v[146:149], v248 offset:1024
	ds_read_b128 v[150:153], v248 offset:2048
	ds_read_b128 v[154:157], v248 offset:3072
	ds_read_b128 v[158:161], v248 offset:4096
	ds_read_b128 v[166:169], v248 offset:5120
	ds_read_b128 v[170:173], v248 offset:6144
	ds_read_b128 v[174:177], v248 offset:7168
	global_load_lds_dwordx4 v[178:179], off
	v_lshl_add_u64 v[178:179], s[30:31], 0, v[208:209]
	s_add_i32 m0, s62, 0xe000
	s_nop 0
	global_load_lds_dwordx4 v[178:179], off
	s_waitcnt lgkmcnt(8)
	s_barrier
	s_waitcnt lgkmcnt(0)
	s_waitcnt lgkmcnt(0)
	v_mfma_f32_16x16x32_f16 v[162:165], v[58:61], v[142:145], v[162:165]
	v_mfma_f32_16x16x32_f16 v[134:137], v[130:133], v[142:145], v[134:137]
	v_mfma_f32_16x16x32_f16 v[118:121], v[58:61], v[150:153], v[118:121]
	v_mfma_f32_16x16x32_f16 v[114:117], v[130:133], v[150:153], v[114:117]
	v_mfma_f32_16x16x32_f16 v[102:105], v[58:61], v[158:161], v[102:105]
	v_mfma_f32_16x16x32_f16 v[98:101], v[130:133], v[158:161], v[98:101]
	v_mfma_f32_16x16x32_f16 v[86:89], v[58:61], v[170:173], v[86:89]
	v_mfma_f32_16x16x32_f16 v[82:85], v[130:133], v[170:173], v[82:85]
	v_mfma_f32_16x16x32_f16 v[162:165], v[66:69], v[146:149], v[162:165]
	v_mfma_f32_16x16x32_f16 v[134:137], v[138:141], v[146:149], v[134:137]
	v_mfma_f32_16x16x32_f16 v[118:121], v[66:69], v[154:157], v[118:121]
	v_mfma_f32_16x16x32_f16 v[114:117], v[138:141], v[154:157], v[114:117]
	v_mfma_f32_16x16x32_f16 v[102:105], v[66:69], v[166:169], v[102:105]
	v_mfma_f32_16x16x32_f16 v[98:101], v[138:141], v[166:169], v[98:101]
	v_mfma_f32_16x16x32_f16 v[86:89], v[66:69], v[174:177], v[86:89]
	v_mfma_f32_16x16x32_f16 v[82:85], v[138:141], v[174:177], v[82:85]
	s_barrier
	s_add_i32 s42, 0, 0x14000
	s_add_i32 s41, s41, s57
	v_add_u32_e32 v190, s42, v246
	v_lshl_add_u64 v[210:211], s[36:37], 0, v[202:203]
	s_mov_b32 m0, s41
	ds_read_b128 v[178:181], v190
	ds_read_b128 v[182:185], v190 offset:1024
	ds_read_b128 v[186:189], v190 offset:2048
	ds_read_b128 v[190:193], v190 offset:3072
	global_load_lds_dwordx4 v[210:211], off
	v_lshl_add_u64 v[212:213], s[36:37], 0, v[204:205]
	s_add_i32 m0, s41, 0x2000
	s_nop 0
	global_load_lds_dwordx4 v[212:213], off
	s_barrier
; #define PG8_STAGE(bufoff, gbase, voff) do { _Pragma("unroll") for (int _i = 0; _i < 2; ++_i) \
;     __builtin_amdgcn_global_load_lds((const unsigned*)((const char*)(gbase) + (voff)[_i]), (LAS unsigned*)(lds + (bufoff) + ldsw + _i * 8192), 16, 0, 0); } while (0)
; #define PG8_LDA(dst, b, h) do { _Pragma("unroll") for (int m = 0; m < 4; ++m) _Pragma("unroll") for (int k = 0; k < 2; ++k) dst[m][k] = *(const LAS bf16x8*)(lds + PG8_SA(b, h) + aoff + m * 2048 + k * 1024); } while (0)
; #define PG8_LDB(dst, b, h) do { _Pragma("unroll") for (int n = 0; n < 2; ++n) _Pragma("unroll") for (int k = 0; k < 2; ++k) dst[n][k] = *(const LAS bf16x8*)(lds + PG8_SB(b, h) + boff + n * 2048 + k * 1024); } while (0)
; #define PG8_WAIT_V(n) asm volatile("s_waitcnt vmcnt(" #n ")" ::: "memory")
; #define PG8_WAIT_L(n) asm volatile("s_waitcnt lgkmcnt(" #n ")" ::: "memory")
; #define PG8_BAR __builtin_amdgcn_s_barrier()
; #define PG8_SCHED __builtin_amdgcn_sched_barrier(0)
; template <class Epi>
; DI void gemm_phase(int wv, LAS unsigned char* lds, const Gemm g, const StaticOrder& S, const Epi& E) {
;     ...
;       PG8_BAR; PG8_WAIT_L(0); PG8_MMA(0, 1, At, B1); PG8_BAR;
;       PG8_LDA(At, 0, 1); PG8_STAGE(PG8_SA(0, 0), a2, voffA);
;       PG8_BAR; PG8_WAIT_L(0); PG8_MMA(1, 0, At, B0); PG8_BAR; PG8_SCHED;
;       PG8_STAGE(PG8_SB(0, 1), b2 + hstep, voffA);
;       PG8_WAIT_V(6); PG8_BAR; PG8_MMA(1, 1, At, B1); PG8_BAR;
;       PG8_LDB(B0, 1, 0); PG8_SCHED; PG8_LDA(At, 1, 0); PG8_STAGE(PG8_SA(0, 1), a2 + hstep, voffA);
;       PG8_WAIT_L(8); PG8_BAR; PG8_WAIT_L(0); PG8_MMA(0, 0, At, B0); PG8_BAR; PG8_SCHED;
	s_waitcnt lgkmcnt(0)
	s_waitcnt lgkmcnt(0)
	v_mfma_f32_16x16x32_f16 v[126:129], v[178:181], v[142:145], v[126:129]
	v_mfma_f32_16x16x32_f16 v[122:125], v[186:189], v[142:145], v[122:125]
	v_mfma_f32_16x16x32_f16 v[110:113], v[178:181], v[150:153], v[110:113]
	v_mfma_f32_16x16x32_f16 v[106:109], v[186:189], v[150:153], v[106:109]
	v_mfma_f32_16x16x32_f16 v[94:97], v[178:181], v[158:161], v[94:97]
	v_mfma_f32_16x16x32_f16 v[90:93], v[186:189], v[158:161], v[90:93]
	v_mfma_f32_16x16x32_f16 v[78:81], v[178:181], v[170:173], v[78:81]
	v_mfma_f32_16x16x32_f16 v[74:77], v[186:189], v[170:173], v[74:77]
	v_mfma_f32_16x16x32_f16 v[126:129], v[182:185], v[146:149], v[126:129]
	v_mfma_f32_16x16x32_f16 v[122:125], v[190:193], v[146:149], v[122:125]
	v_mfma_f32_16x16x32_f16 v[110:113], v[182:185], v[154:157], v[110:113]
	v_mfma_f32_16x16x32_f16 v[106:109], v[190:193], v[154:157], v[106:109]
	v_mfma_f32_16x16x32_f16 v[94:97], v[182:185], v[166:169], v[94:97]
	v_mfma_f32_16x16x32_f16 v[90:93], v[190:193], v[166:169], v[90:93]
	v_mfma_f32_16x16x32_f16 v[78:81], v[182:185], v[174:177], v[78:81]
	v_mfma_f32_16x16x32_f16 v[74:77], v[190:193], v[174:177], v[74:77]
	s_mov_b32 m0, s62
	v_lshl_add_u64 v[214:215], s[34:35], 0, v[202:203]
	s_barrier
	ds_read_b128 v[142:145], v248 offset:16384
	ds_read_b128 v[146:149], v248 offset:17408
	ds_read_b128 v[150:153], v248 offset:18432
	ds_read_b128 v[154:157], v248 offset:19456
	ds_read_b128 v[158:161], v248 offset:20480
	ds_read_b128 v[166:169], v248 offset:21504
	ds_read_b128 v[170:173], v248 offset:22528
	ds_read_b128 v[174:177], v248 offset:23552
	global_load_lds_dwordx4 v[214:215], off
	v_lshl_add_u64 v[216:217], s[34:35], 0, v[204:205]
	s_mov_b32 m0, s64
	s_nop 0
	global_load_lds_dwordx4 v[216:217], off
	s_barrier
	s_waitcnt lgkmcnt(0)
	s_waitcnt lgkmcnt(0)
	v_mfma_f32_16x16x32_f16 v[70:73], v[58:61], v[142:145], v[70:73]
	v_mfma_f32_16x16x32_f16 v[62:65], v[130:133], v[142:145], v[62:65]
	v_mfma_f32_16x16x32_f16 v[46:49], v[58:61], v[150:153], v[46:49]
	v_mfma_f32_16x16x32_f16 v[42:45], v[130:133], v[150:153], v[42:45]
	v_mfma_f32_16x16x32_f16 v[28:31], v[58:61], v[158:161], v[28:31]
	v_mfma_f32_16x16x32_f16 v[24:27], v[130:133], v[158:161], v[24:27]
	v_mfma_f32_16x16x32_f16 v[12:15], v[58:61], v[170:173], v[12:15]
	v_mfma_f32_16x16x32_f16 v[8:11], v[130:133], v[170:173], v[8:11]
	v_mfma_f32_16x16x32_f16 v[70:73], v[66:69], v[146:149], v[70:73]
	v_mfma_f32_16x16x32_f16 v[62:65], v[138:141], v[146:149], v[62:65]
	v_mfma_f32_16x16x32_f16 v[46:49], v[66:69], v[154:157], v[46:49]
	v_mfma_f32_16x16x32_f16 v[42:45], v[138:141], v[154:157], v[42:45]
	v_mfma_f32_16x16x32_f16 v[28:31], v[66:69], v[166:169], v[28:31]
	v_mfma_f32_16x16x32_f16 v[24:27], v[138:141], v[166:169], v[24:27]
	v_mfma_f32_16x16x32_f16 v[12:15], v[66:69], v[174:177], v[12:15]
	v_mfma_f32_16x16x32_f16 v[8:11], v[138:141], v[174:177], v[8:11]
	s_barrier
	s_add_u32 s36, s36, s84
	s_addc_u32 s37, s37, 0
	s_add_i32 s41, s42, s57
	v_lshl_add_u64 v[218:219], s[36:37], 0, v[202:203]
	s_mov_b32 m0, s41
	v_lshl_add_u64 v[220:221], s[36:37], 0, v[204:205]
	global_load_lds_dwordx4 v[218:219], off
	s_add_i32 m0, s41, 0x2000
	s_nop 0
	global_load_lds_dwordx4 v[220:221], off
	s_waitcnt vmcnt(6)
	s_barrier
	v_mfma_f32_16x16x32_f16 v[54:57], v[178:181], v[142:145], v[54:57]
	v_mfma_f32_16x16x32_f16 v[50:53], v[186:189], v[142:145], v[50:53]
	v_mfma_f32_16x16x32_f16 v[38:41], v[178:181], v[150:153], v[38:41]
	v_mfma_f32_16x16x32_f16 v[34:37], v[186:189], v[150:153], v[34:37]
	v_mfma_f32_16x16x32_f16 v[20:23], v[178:181], v[158:161], v[20:23]
	v_mfma_f32_16x16x32_f16 v[16:19], v[186:189], v[158:161], v[16:19]
	v_mfma_f32_16x16x32_f16 v[4:7], v[178:181], v[170:173], v[4:7]
	v_mfma_f32_16x16x32_f16 v[0:3], v[186:189], v[170:173], v[0:3]
	v_mfma_f32_16x16x32_f16 v[54:57], v[182:185], v[146:149], v[54:57]
	v_mfma_f32_16x16x32_f16 v[50:53], v[190:193], v[146:149], v[50:53]
	v_mfma_f32_16x16x32_f16 v[38:41], v[182:185], v[154:157], v[38:41]
	v_mfma_f32_16x16x32_f16 v[34:37], v[190:193], v[154:157], v[34:37]
	v_mfma_f32_16x16x32_f16 v[20:23], v[182:185], v[166:169], v[20:23]
	v_mfma_f32_16x16x32_f16 v[16:19], v[190:193], v[166:169], v[16:19]
	v_mfma_f32_16x16x32_f16 v[4:7], v[182:185], v[174:177], v[4:7]
	v_mfma_f32_16x16x32_f16 v[0:3], v[190:193], v[174:177], v[0:3]
	s_add_i32 s36, 0, 0x18000
	v_add_u32_e32 v138, s36, v246
	s_barrier
	ds_read_b128 v[58:61], v138
	ds_read_b128 v[66:69], v138 offset:1024
	ds_read_b128 v[130:133], v138 offset:2048
	ds_read_b128 v[138:141], v138 offset:3072
	s_add_u32 s34, s34, s84
	s_addc_u32 s35, s35, 0
	s_mov_b32 m0, s65
	v_lshl_add_u64 v[178:179], s[34:35], 0, v[202:203]
	ds_read_b128 v[142:145], v248 offset:32768
	ds_read_b128 v[146:149], v248 offset:33792
	ds_read_b128 v[150:153], v248 offset:34816
	ds_read_b128 v[154:157], v248 offset:35840
	ds_read_b128 v[158:161], v248 offset:36864
	ds_read_b128 v[166:169], v248 offset:37888
	ds_read_b128 v[170:173], v248 offset:38912
	ds_read_b128 v[174:177], v248 offset:39936
	global_load_lds_dwordx4 v[178:179], off
	v_lshl_add_u64 v[178:179], s[34:35], 0, v[204:205]
	s_mov_b32 m0, s70
	s_nop 0
	global_load_lds_dwordx4 v[178:179], off
	s_waitcnt lgkmcnt(8)
	s_barrier
; #define PG8_STAGE(bufoff, gbase, voff) do { _Pragma("unroll") for (int _i = 0; _i < 2; ++_i) \
;     __builtin_amdgcn_global_load_lds((const unsigned*)((const char*)(gbase) + (voff)[_i]), (LAS unsigned*)(lds + (bufoff) + ldsw + _i * 8192), 16, 0, 0); } while (0)
; #define PG8_LDA(dst, b, h) do { _Pragma("unroll") for (int m = 0; m < 4; ++m) _Pragma("unroll") for (int k = 0; k < 2; ++k) dst[m][k] = *(const LAS bf16x8*)(lds + PG8_SA(b, h) + aoff + m * 2048 + k * 1024); } while (0)
; #define PG8_LDB(dst, b, h) do { _Pragma("unroll") for (int n = 0; n < 2; ++n) _Pragma("unroll") for (int k = 0; k < 2; ++k) dst[n][k] = *(const LAS bf16x8*)(lds + PG8_SB(b, h) + boff + n * 2048 + k * 1024); } while (0)
; #define PG8_WAIT_V(n) asm volatile("s_waitcnt vmcnt(" #n ")" ::: "memory")
; #define PG8_WAIT_L(n) asm volatile("s_waitcnt lgkmcnt(" #n ")" ::: "memory")
; #define PG8_BAR __builtin_amdgcn_s_barrier()
; #define PG8_SCHED __builtin_amdgcn_sched_barrier(0)
; template <class Epi>
; DI void gemm_phase(int wv, LAS unsigned char* lds, const Gemm g, const StaticOrder& S, const Epi& E) {
;     ...
;       PG8_WAIT_L(8); PG8_BAR; PG8_WAIT_L(0); PG8_MMA(0, 0, At, B0); PG8_BAR; PG8_SCHED;
;       PG8_LDB(B1, 1, 1); PG8_STAGE(PG8_SB(1, 0), b3, voffA);
;       PG8_BAR; PG8_WAIT_L(0); PG8_MMA(0, 1, At, B1); PG8_BAR;
;       PG8_LDA(At, 1, 1); PG8_STAGE(PG8_SA(1, 0), a3, voffA);
;       PG8_BAR; PG8_WAIT_L(0); PG8_MMA(1, 0, At, B0); PG8_BAR; PG8_SCHED;
;       PG8_STAGE(PG8_SB(1, 1), b3 + hstep, voffA);
;       PG8_WAIT_V(6); PG8_BAR; PG8_MMA(1, 1, At, B1); PG8_BAR;
	s_waitcnt lgkmcnt(0)
	s_waitcnt lgkmcnt(0)
	v_mfma_f32_16x16x32_f16 v[162:165], v[58:61], v[142:145], v[162:165]
	v_mfma_f32_16x16x32_f16 v[134:137], v[130:133], v[142:145], v[134:137]
	v_mfma_f32_16x16x32_f16 v[118:121], v[58:61], v[150:153], v[118:121]
	v_mfma_f32_16x16x32_f16 v[114:117], v[130:133], v[150:153], v[114:117]
	v_mfma_f32_16x16x32_f16 v[102:105], v[58:61], v[158:161], v[102:105]
	v_mfma_f32_16x16x32_f16 v[98:101], v[130:133], v[158:161], v[98:101]
	v_mfma_f32_16x16x32_f16 v[86:89], v[58:61], v[170:173], v[86:89]
	v_mfma_f32_16x16x32_f16 v[82:85], v[130:133], v[170:173], v[82:85]
	v_mfma_f32_16x16x32_f16 v[162:165], v[66:69], v[146:149], v[162:165]
	v_mfma_f32_16x16x32_f16 v[134:137], v[138:141], v[146:149], v[134:137]
	v_mfma_f32_16x16x32_f16 v[118:121], v[66:69], v[154:157], v[118:121]
	v_mfma_f32_16x16x32_f16 v[114:117], v[138:141], v[154:157], v[114:117]
	v_mfma_f32_16x16x32_f16 v[102:105], v[66:69], v[166:169], v[102:105]
	v_mfma_f32_16x16x32_f16 v[98:101], v[138:141], v[166:169], v[98:101]
	v_mfma_f32_16x16x32_f16 v[86:89], v[66:69], v[174:177], v[86:89]
	v_mfma_f32_16x16x32_f16 v[82:85], v[138:141], v[174:177], v[82:85]
	s_barrier
	s_add_i32 s34, 0, 0x1c000
	s_add_i32 s35, s36, s57
	v_add_u32_e32 v190, s34, v246
	v_lshl_add_u64 v[210:211], v[210:211], 0, s[2:3]
	s_mov_b32 m0, s35
	ds_read_b128 v[178:181], v190
	ds_read_b128 v[182:185], v190 offset:1024
	ds_read_b128 v[186:189], v190 offset:2048
	ds_read_b128 v[190:193], v190 offset:3072
	global_load_lds_dwordx4 v[210:211], off
	v_lshl_add_u64 v[210:211], v[212:213], 0, s[2:3]
	s_add_i32 m0, s35, 0x2000
	s_nop 0
	global_load_lds_dwordx4 v[210:211], off
	s_barrier
	s_waitcnt lgkmcnt(0)
	s_waitcnt lgkmcnt(0)
	v_mfma_f32_16x16x32_f16 v[126:129], v[178:181], v[142:145], v[126:129]
	v_mfma_f32_16x16x32_f16 v[122:125], v[186:189], v[142:145], v[122:125]
	v_mfma_f32_16x16x32_f16 v[110:113], v[178:181], v[150:153], v[110:113]
	v_mfma_f32_16x16x32_f16 v[106:109], v[186:189], v[150:153], v[106:109]
	v_mfma_f32_16x16x32_f16 v[94:97], v[178:181], v[158:161], v[94:97]
	v_mfma_f32_16x16x32_f16 v[90:93], v[186:189], v[158:161], v[90:93]
	v_mfma_f32_16x16x32_f16 v[78:81], v[178:181], v[170:173], v[78:81]
	v_mfma_f32_16x16x32_f16 v[74:77], v[186:189], v[170:173], v[74:77]
	v_mfma_f32_16x16x32_f16 v[126:129], v[182:185], v[146:149], v[126:129]
	v_mfma_f32_16x16x32_f16 v[122:125], v[190:193], v[146:149], v[122:125]
	v_mfma_f32_16x16x32_f16 v[110:113], v[182:185], v[154:157], v[110:113]
	v_mfma_f32_16x16x32_f16 v[106:109], v[190:193], v[154:157], v[106:109]
	v_mfma_f32_16x16x32_f16 v[94:97], v[182:185], v[166:169], v[94:97]
	v_mfma_f32_16x16x32_f16 v[90:93], v[190:193], v[166:169], v[90:93]
	v_mfma_f32_16x16x32_f16 v[78:81], v[182:185], v[174:177], v[78:81]
	v_mfma_f32_16x16x32_f16 v[74:77], v[190:193], v[174:177], v[74:77]
	s_mov_b32 m0, s71
	v_lshl_add_u64 v[210:211], v[214:215], 0, s[2:3]
	s_barrier
	ds_read_b128 v[142:145], v248 offset:49152
	ds_read_b128 v[146:149], v248 offset:50176
	ds_read_b128 v[150:153], v248 offset:51200
	ds_read_b128 v[154:157], v248 offset:52224
	ds_read_b128 v[158:161], v248 offset:53248
	ds_read_b128 v[166:169], v248 offset:54272
	ds_read_b128 v[170:173], v248 offset:55296
	ds_read_b128 v[174:177], v248 offset:56320
	global_load_lds_dwordx4 v[210:211], off
	v_lshl_add_u64 v[210:211], v[216:217], 0, s[2:3]
	s_mov_b32 m0, s82
	s_nop 0
	global_load_lds_dwordx4 v[210:211], off
	s_barrier
	s_waitcnt lgkmcnt(0)
	s_waitcnt lgkmcnt(0)
	v_mfma_f32_16x16x32_f16 v[70:73], v[58:61], v[142:145], v[70:73]
	v_mfma_f32_16x16x32_f16 v[62:65], v[130:133], v[142:145], v[62:65]
	v_mfma_f32_16x16x32_f16 v[46:49], v[58:61], v[150:153], v[46:49]
	v_mfma_f32_16x16x32_f16 v[42:45], v[130:133], v[150:153], v[42:45]
	v_mfma_f32_16x16x32_f16 v[28:31], v[58:61], v[158:161], v[28:31]
	v_mfma_f32_16x16x32_f16 v[24:27], v[130:133], v[158:161], v[24:27]
	v_mfma_f32_16x16x32_f16 v[12:15], v[58:61], v[170:173], v[12:15]
	v_mfma_f32_16x16x32_f16 v[8:11], v[130:133], v[170:173], v[8:11]
	v_mfma_f32_16x16x32_f16 v[70:73], v[66:69], v[146:149], v[70:73]
	v_mfma_f32_16x16x32_f16 v[62:65], v[138:141], v[146:149], v[62:65]
	v_mfma_f32_16x16x32_f16 v[46:49], v[66:69], v[154:157], v[46:49]
	v_mfma_f32_16x16x32_f16 v[42:45], v[138:141], v[154:157], v[42:45]
	v_mfma_f32_16x16x32_f16 v[28:31], v[66:69], v[166:169], v[28:31]
	v_mfma_f32_16x16x32_f16 v[24:27], v[138:141], v[166:169], v[24:27]
	v_mfma_f32_16x16x32_f16 v[12:15], v[66:69], v[174:177], v[12:15]
	v_mfma_f32_16x16x32_f16 v[8:11], v[138:141], v[174:177], v[8:11]
	s_barrier
	s_add_i32 s34, s34, s57
	v_lshl_add_u64 v[58:59], v[218:219], 0, s[2:3]
	s_mov_b32 m0, s34
	s_nop 0
	global_load_lds_dwordx4 v[58:59], off
	v_lshl_add_u64 v[58:59], v[220:221], 0, s[2:3]
	s_add_i32 m0, s34, 0x2000
	s_nop 0
	global_load_lds_dwordx4 v[58:59], off
	s_waitcnt vmcnt(6)
	s_barrier
	v_mfma_f32_16x16x32_f16 v[54:57], v[178:181], v[142:145], v[54:57]
	v_mfma_f32_16x16x32_f16 v[50:53], v[186:189], v[142:145], v[50:53]
	v_mfma_f32_16x16x32_f16 v[38:41], v[178:181], v[150:153], v[38:41]
	v_mfma_f32_16x16x32_f16 v[34:37], v[186:189], v[150:153], v[34:37]
	v_mfma_f32_16x16x32_f16 v[20:23], v[178:181], v[158:161], v[20:23]
	v_mfma_f32_16x16x32_f16 v[16:19], v[186:189], v[158:161], v[16:19]
	v_mfma_f32_16x16x32_f16 v[4:7], v[178:181], v[170:173], v[4:7]
	v_mfma_f32_16x16x32_f16 v[0:3], v[186:189], v[170:173], v[0:3]
	v_mfma_f32_16x16x32_f16 v[54:57], v[182:185], v[146:149], v[54:57]
	v_mfma_f32_16x16x32_f16 v[50:53], v[190:193], v[146:149], v[50:53]
	v_mfma_f32_16x16x32_f16 v[38:41], v[182:185], v[154:157], v[38:41]
	v_mfma_f32_16x16x32_f16 v[34:37], v[190:193], v[154:157], v[34:37]
	v_mfma_f32_16x16x32_f16 v[20:23], v[182:185], v[166:169], v[20:23]
	v_mfma_f32_16x16x32_f16 v[16:19], v[190:193], v[166:169], v[16:19]
	v_mfma_f32_16x16x32_f16 v[4:7], v[182:185], v[174:177], v[4:7]
	v_mfma_f32_16x16x32_f16 v[0:3], v[190:193], v[174:177], v[0:3]
	s_add_u32 s30, s30, 0x100
	s_addc_u32 s31, s31, 0
	s_add_u32 s95, s95, 0x100
	s_addc_u32 vcc_lo, vcc_lo, 0
	s_cmp_ge_u32 vcc_hi, s51
	s_mov_b32 s34, vcc_hi
	s_barrier
; #define LAS __attribute__((address_space(3)))
; DI unsigned pkh2(float a, float b) { typedef _Float16 h2 __attribute__((ext_vector_type(2))); h2 v; v[0] = (_Float16)a; v[1] = (_Float16)b; return __builtin_bit_cast(unsigned, v); }
;   DI void operator()(const f32x4 (&acc)[2][2][4][2], const pg8::Unit& u, int wr, int wc, int fr, int fq, LAS unsigned char* lds, int ui, int wid) const {
;     const int col0 = u.pn * 256 + wc * 32 + 8 * fq;
;     int fq_ = fq, fr_ = fr; asm volatile("" : "+v"(fq_), "+v"(fr_));
;     const LAS float* gl = (const LAS float*)(lds + 139264 + (ui & 1) * 3072) + wc * 32 + 8 * fq_;
;     const LAS float* sl = (const LAS float*)(lds + 131072 + wid * 1024);
;     float rmu[8], rrs[8];
; #pragma unroll
;     for (int i = 0; i < 8; ++i) { typedef float f32x2_ __attribute__((ext_vector_type(2))); const f32x2_ sv = *(const LAS f32x2_*)(sl + (i >> 2) * 128 + ((i & 3) * 16 + fr_) * 2);
;       const float mu = sv.x * (1.0f / 1024.0f), var = fmaxf(sv.y * (1.0f / 1024.0f) - mu * mu, 0.f); rmu[i] = mu; rrs[i] = rsqrtf(var + 1e-5f); }
; #pragma unroll
;     for (int ai = 0; ai < 2; ++ai) {
;       half8 tpv[4][2];
; #pragma unroll
;       for (int m = 0; m < 4; ++m)
; #pragma unroll
;         for (int bj = 0; bj < 2; ++bj) tpv[m][bj] = *(const half8*)(tb + (size_t)(u.pm * 256 + ai * 128 + wr * 64 + m * 16 + fr) * DM + col0 + bj * 128);
; #pragma unroll
;       for (int m = 0; m < 4; ++m) {
;         const int row = u.pm * 256 + ai * 128 + wr * 64 + m * 16 + fr; const float mu = rmu[ai * 4 + m], rstd = rrs[ai * 4 + m];
;         float rs = 0.f, rq = 0.f;
; #pragma unroll
;         for (int bj = 0; bj < 2; ++bj) {
;           u32x4 w;
; #pragma unroll
;           for (int n = 0; n < 2; ++n) {
;             f32x4 tp;
; #pragma unroll
;             for (int j = 0; j < 4; ++j) tp[j] = (float)tpv[m][bj][4 * n + j];
;             tp = (tp - mu) * rstd * (*(const LAS f32x4*)(gl + bj * 128 + 4 * n)) + *(const LAS f32x4*)(gl + 256 + bj * 128 + 4 * n);
;             const f32x4 tn = tp * ALPHA + acc[ai][bj][m][n] * scale;
;             w[2 * n] = pkh2(tn[0], tn[1]); w[2 * n + 1] = pkh2(tn[2], tn[3]);
;             rs += tn[0] + tn[1] + tn[2] + tn[3]; rq += tn[0] * tn[0] + tn[1] * tn[1] + tn[2] * tn[2] + tn[3] * tn[3];
;           }
;           *(u32x4*)(tb + (size_t)row * DM + col0 + bj * 128) = w;
;         }
	s_cbranch_scc0 .LBB0_890
	v_mov_b32_e32 v58, v243
	v_mov_b32_e32 v59, v244
	s_mov_b32 s36, 0x800000
	v_lshlrev_b32_e32 v138, 5, v58
	v_lshl_add_u32 v58, v59, 3, s63
	ds_read2_b64 v[168:171], v58 offset1:16
	s_bitcmp1_b32 s94, 0
	v_lshl_add_u32 v212, s78, 8, v245
	s_cselect_b32 s30, 0xc00, 0
	v_or_b32_e32 v220, 32, v212
	s_waitcnt lgkmcnt(0)
	v_pk_mul_f32 v[192:193], v[168:169], s[44:45] op_sel_hi:[1,0]
	s_add_i32 s30, s86, s30
	v_fma_f32 v59, -v192, v192, v193
	v_max_f32_e32 v59, 0, v59
	v_add_f32_e32 v59, 0x3727c5ac, v59
	v_cmp_gt_f32_e32 vcc, s36, v59
	v_mul_f32_e32 v60, 0x4b800000, v59
	v_ashrrev_i32_e32 v221, 31, v220
	v_cndmask_b32_e32 v59, v59, v60, vcc
	v_rsq_f32_e32 v59, v59
	v_and_b32_e32 v139, 64, v240
	v_lshlrev_b64 v[222:223], 11, v[220:221]
	v_add_u32_e32 v221, s30, v138
	v_mul_f32_e32 v60, 0x45800000, v59
	v_xor_b32_e32 v138, 16, v240
	v_add_u32_e32 v139, 64, v139
	v_or_b32_e32 v214, 48, v212
	v_cndmask_b32_e32 v228, v59, v60, vcc
	v_cmp_lt_i32_e32 vcc, v138, v139
	v_lshl_or_b32 v210, s79, 8, v247
	v_ashrrev_i32_e32 v215, 31, v214
	v_cndmask_b32_e32 v138, v240, v138, vcc
	v_ashrrev_i32_e32 v211, 31, v210
	v_lshlrev_b64 v[218:219], 11, v[214:215]
	v_lshlrev_b32_e32 v215, 2, v138
	v_xor_b32_e32 v138, 32, v240
	v_ashrrev_i32_e32 v213, 31, v212
	v_cmp_lt_i32_e32 vcc, v138, v139
	v_lshlrev_b64 v[190:191], 1, v[210:211]
	v_lshlrev_b64 v[184:185], 11, v[212:213]
	v_cndmask_b32_e32 v138, v240, v138, vcc
	v_lshl_add_u64 v[216:217], s[76:77], 0, v[190:191]
	v_lshlrev_b32_e32 v213, 2, v138
	v_lshl_add_u64 v[138:139], v[216:217], 0, v[184:185]
	ds_read2_b64 v[130:133], v58 offset0:32 offset1:48
	ds_read2_b64 v[66:69], v58 offset0:64 offset1:80
	ds_read2_b64 v[58:61], v58 offset0:96 offset1:112
	global_load_dwordx4 v[180:183], v[138:139], off
	global_load_dwordx4 v[186:189], v[138:139], off offset:256
	v_or_b32_e32 v224, 16, v212
	v_ashrrev_i32_e32 v225, 31, v224
	v_lshlrev_b64 v[226:227], 11, v[224:225]
	v_lshl_add_u64 v[138:139], v[216:217], 0, v[226:227]
	global_load_dwordx4 v[176:179], v[138:139], off
	global_load_dwordx4 v[172:175], v[138:139], off offset:256
	v_lshl_add_u64 v[138:139], v[216:217], 0, v[222:223]
	global_load_dwordx4 v[166:169], v[138:139], off
	global_load_dwordx4 v[158:161], v[138:139], off offset:256
	v_lshl_add_u64 v[138:139], v[216:217], 0, v[218:219]
	global_load_dwordx4 v[142:145], v[138:139], off
	s_nop 0
	global_load_dwordx4 v[138:141], v[138:139], off offset:256
	s_waitcnt vmcnt(7)
	v_cvt_f32_f16_sdwa v149, v180 dst_sel:DWORD dst_unused:UNUSED_PAD src0_sel:WORD_1
	v_cvt_f32_f16_e32 v148, v180
	v_cvt_f32_f16_sdwa v147, v181 dst_sel:DWORD dst_unused:UNUSED_PAD src0_sel:WORD_1
	v_cvt_f32_f16_e32 v146, v181
	v_sub_f32_e32 v149, v149, v192
	v_sub_f32_e32 v148, v148, v192
	v_sub_f32_e32 v147, v147, v192
	v_sub_f32_e32 v146, v146, v192
	v_pk_mul_f32 v[180:181], v[228:229], v[148:149] op_sel_hi:[0,1]
	v_pk_mul_f32 v[230:231], v[228:229], v[146:147] op_sel_hi:[0,1]
	ds_read_b128 v[150:153], v221
	ds_read_b128 v[146:149], v221 offset:16
	ds_read_b128 v[154:157], v221 offset:1024
	s_waitcnt lgkmcnt(0)
	v_pk_fma_f32 v[180:181], v[180:181], v[150:151], v[154:155]
	s_nop 0
	v_pk_mul_f32 v[180:181], v[180:181], s[52:53] op_sel_hi:[1,0]
	v_pk_fma_f32 v[230:231], v[230:231], v[152:153], v[156:157]
	v_pk_fma_f32 v[162:163], s[12:13], v[162:163], v[180:181]
	v_pk_mul_f32 v[230:231], v[230:231], s[52:53] op_sel_hi:[1,0]
	v_mul_f32_e32 v225, v163, v163
	v_pk_fma_f32 v[164:165], s[14:15], v[164:165], v[230:231]
	v_add_f32_e32 v193, v162, v163
	v_fmac_f32_e32 v225, v162, v162
	v_add_f32_e32 v193, v164, v193
	v_fmac_f32_e32 v225, v164, v164
	v_cvt_pk_f16_f32 v180, v162, v163
	v_cvt_pk_f16_f32 v181, v164, v165
	v_add_f32_e32 v193, v165, v193
	v_fmac_f32_e32 v225, v165, v165
	v_cvt_f32_f16_sdwa v165, v182 dst_sel:DWORD dst_unused:UNUSED_PAD src0_sel:WORD_1
	v_cvt_f32_f16_e32 v164, v182
	v_cvt_f32_f16_sdwa v163, v183 dst_sel:DWORD dst_unused:UNUSED_PAD src0_sel:WORD_1
	v_cvt_f32_f16_e32 v162, v183
	v_sub_f32_e32 v165, v165, v192
	v_sub_f32_e32 v164, v164, v192
	v_sub_f32_e32 v163, v163, v192
	v_sub_f32_e32 v162, v162, v192
	v_pk_mul_f32 v[182:183], v[228:229], v[164:165] op_sel_hi:[0,1]
	v_pk_mul_f32 v[230:231], v[228:229], v[162:163] op_sel_hi:[0,1]
	ds_read_b128 v[162:165], v221 offset:1040
	v_add_f32_e32 v193, 0, v193
	s_waitcnt lgkmcnt(0)
; #define LAS __attribute__((address_space(3)))
; DI unsigned pkh2(float a, float b) { typedef _Float16 h2 __attribute__((ext_vector_type(2))); h2 v; v[0] = (_Float16)a; v[1] = (_Float16)b; return __builtin_bit_cast(unsigned, v); }
;   DI void operator()(const f32x4 (&acc)[2][2][4][2], const pg8::Unit& u, int wr, int wc, int fr, int fq, LAS unsigned char* lds, int ui, int wid) const {
;     ...
;           for (int n = 0; n < 2; ++n) {
;             f32x4 tp;
; #pragma unroll
;             for (int j = 0; j < 4; ++j) tp[j] = (float)tpv[m][bj][4 * n + j];
;             tp = (tp - mu) * rstd * (*(const LAS f32x4*)(gl + bj * 128 + 4 * n)) + *(const LAS f32x4*)(gl + 256 + bj * 128 + 4 * n);
;             const f32x4 tn = tp * ALPHA + acc[ai][bj][m][n] * scale;
;             w[2 * n] = pkh2(tn[0], tn[1]); w[2 * n + 1] = pkh2(tn[2], tn[3]);
;             rs += tn[0] + tn[1] + tn[2] + tn[3]; rq += tn[0] * tn[0] + tn[1] * tn[1] + tn[2] * tn[2] + tn[3] * tn[3];
;           }
;           *(u32x4*)(tb + (size_t)row * DM + col0 + bj * 128) = w;
;         }
;         rs += __shfl_xor(rs, 16); rs += __shfl_xor(rs, 32); rq += __shfl_xor(rq, 16); rq += __shfl_xor(rq, 32);
;         if (fq == 0) { atomicAdd(stats_new + 2 * row, rs); atomicAdd(stats_new + 2 * row + 1, rq); }
	v_pk_fma_f32 v[182:183], v[182:183], v[146:147], v[162:163]
	v_pk_fma_f32 v[230:231], v[230:231], v[148:149], v[164:165]
	v_pk_mul_f32 v[182:183], v[182:183], s[52:53] op_sel_hi:[1,0]
	v_pk_mul_f32 v[230:231], v[230:231], s[52:53] op_sel_hi:[1,0]
	v_pk_fma_f32 v[134:135], s[12:13], v[134:135], v[182:183]
	v_pk_fma_f32 v[136:137], s[14:15], v[136:137], v[230:231]
	v_cvt_pk_f16_f32 v182, v134, v135
	v_add_f32_e32 v230, v134, v135
	v_mul_f32_e32 v135, v135, v135
	v_fmac_f32_e32 v135, v134, v134
	v_fmac_f32_e32 v135, v136, v136
	v_add_f32_e32 v230, v136, v230
	v_fmac_f32_e32 v135, v137, v137
	v_add_f32_e32 v230, v137, v230
	v_add_f32_e32 v225, v225, v135
	v_lshl_add_u64 v[134:135], s[76:77], 0, v[184:185]
	v_cvt_pk_f16_f32 v183, v136, v137
	v_add_f32_e32 v193, v193, v230
	v_lshl_add_u64 v[230:231], v[134:135], 0, v[190:191]
	s_waitcnt vmcnt(6)
	v_cvt_f32_f16_sdwa v137, v186 dst_sel:DWORD dst_unused:UNUSED_PAD src0_sel:WORD_1
	v_cvt_f32_f16_e32 v136, v186
	v_cvt_f32_f16_sdwa v135, v187 dst_sel:DWORD dst_unused:UNUSED_PAD src0_sel:WORD_1
	v_cvt_f32_f16_e32 v134, v187
	global_store_dwordx4 v[230:231], v[180:183], off
	v_sub_f32_e32 v136, v136, v192
	v_sub_f32_e32 v135, v135, v192
	v_sub_f32_e32 v134, v134, v192
	v_sub_f32_e32 v137, v137, v192
	v_pk_mul_f32 v[190:191], v[228:229], v[136:137] op_sel_hi:[0,1]
	v_pk_mul_f32 v[250:251], v[228:229], v[134:135] op_sel_hi:[0,1]
	ds_read_b128 v[180:183], v221 offset:512
	ds_read_b128 v[134:137], v221 offset:528
	ds_read_b128 v[184:187], v221 offset:1536
	s_waitcnt lgkmcnt(0)
	v_pk_fma_f32 v[190:191], v[190:191], v[180:181], v[184:185]
	s_nop 0
	v_pk_mul_f32 v[190:191], v[190:191], s[52:53] op_sel_hi:[1,0]
	v_pk_fma_f32 v[250:251], v[250:251], v[182:183], v[186:187]
	v_pk_fma_f32 v[126:127], s[12:13], v[126:127], v[190:191]
	v_pk_mul_f32 v[250:251], v[250:251], s[52:53] op_sel_hi:[1,0]
	v_cvt_pk_f16_f32 v190, v126, v127
	v_add_f32_e32 v249, v126, v127
	v_mul_f32_e32 v127, v127, v127
	v_pk_fma_f32 v[128:129], s[14:15], v[128:129], v[250:251]
	v_fmac_f32_e32 v127, v126, v126
	v_fmac_f32_e32 v127, v128, v128
	v_add_f32_e32 v249, v128, v249
	v_fmac_f32_e32 v127, v129, v129
	v_cvt_pk_f16_f32 v191, v128, v129
	v_add_f32_e32 v249, v129, v249
	v_add_f32_e32 v225, v225, v127
	v_cvt_f32_f16_sdwa v129, v188 dst_sel:DWORD dst_unused:UNUSED_PAD src0_sel:WORD_1
	v_cvt_f32_f16_e32 v128, v188
	v_cvt_f32_f16_sdwa v127, v189 dst_sel:DWORD dst_unused:UNUSED_PAD src0_sel:WORD_1
	v_cvt_f32_f16_e32 v126, v189
	v_sub_f32_e32 v129, v129, v192
	v_sub_f32_e32 v128, v128, v192
	v_sub_f32_e32 v127, v127, v192
	v_sub_f32_e32 v126, v126, v192
	v_add_f32_e32 v249, v193, v249
	v_pk_mul_f32 v[188:189], v[228:229], v[128:129] op_sel_hi:[0,1]
	v_pk_mul_f32 v[192:193], v[228:229], v[126:127] op_sel_hi:[0,1]
	ds_read_b128 v[126:129], v221 offset:1552
	s_waitcnt lgkmcnt(0)
	v_pk_fma_f32 v[188:189], v[188:189], v[134:135], v[126:127]
	v_pk_fma_f32 v[192:193], v[192:193], v[136:137], v[128:129]
	v_pk_mul_f32 v[188:189], v[188:189], s[52:53] op_sel_hi:[1,0]
	v_pk_mul_f32 v[192:193], v[192:193], s[52:53] op_sel_hi:[1,0]
	v_pk_fma_f32 v[122:123], s[12:13], v[122:123], v[188:189]
	v_pk_fma_f32 v[124:125], s[14:15], v[124:125], v[192:193]
	v_cvt_pk_f16_f32 v192, v122, v123
	v_add_f32_e32 v188, v122, v123
	v_mul_f32_e32 v123, v123, v123
	v_fmac_f32_e32 v123, v122, v122
	v_add_f32_e32 v188, v124, v188
	v_fmac_f32_e32 v123, v124, v124
	v_add_f32_e32 v188, v125, v188
	v_fmac_f32_e32 v123, v125, v125
	v_cvt_pk_f16_f32 v193, v124, v125
	v_add_f32_e32 v188, v249, v188
	v_add_f32_e32 v124, v225, v123
	v_mov_b32_e32 v122, v188
	v_mov_b32_e32 v125, v124
	global_store_dwordx4 v[230:231], v[190:193], off offset:256
	s_nop 1
	v_permlane16_swap_b32_e32 v122, v188
	v_permlane16_swap_b32_e32 v125, v124
	v_add_f32_e32 v122, v188, v122
	s_waitcnt lgkmcnt(0)
	v_add_f32_e32 v124, v124, v125
	v_mov_b32_e32 v123, v122
	v_mov_b32_e32 v125, v124
	s_nop 1
	v_permlane32_swap_b32_e32 v123, v122
	v_permlane32_swap_b32_e32 v125, v124
	s_and_saveexec_b64 s[30:31], s[6:7]
	s_cbranch_execz .LBB0_893
	v_lshlrev_b32_e32 v188, 1, v212
	v_ashrrev_i32_e32 v189, 31, v188
	v_lshl_add_u64 v[188:189], v[188:189], 2, s[16:17]
	s_waitcnt lgkmcnt(1)
	v_add_f32_e32 v122, v122, v123
	s_waitcnt lgkmcnt(0)
	v_add_f32_e32 v123, v124, v125
	global_atomic_add_f32 v[188:189], v122, off
	global_atomic_add_f32 v[188:189], v123, off offset:4
